# balance the mix phase: lower grid half takes two gMLP items (upper half has the memory-K/V tile); dead denormal-scaling ops removed from the stick-breaking scan (bit-exact); MoE tile-boundary load bat
# speedup vs baseline: 1.0386x; 1.0386x over previous
; __device__ void attn_item(const Params& p, int h, int qt, u16* smem) {
;     ...
;         qf[mt][ks] = *(const bf16x8*)(Qb + (long)(q0 + w * 32 + mt * 16 + fr) * INW + ks * 32 + fq * 8);
; #pragma unroll
;     for (int i = 0; i < 4; i++) {
;       int idx = t + 256 * i;
;       int key = idx >> 4, ch = idx & 15;
;       uint4 kv = *(const uint4*)(Kb + (long)(kb * 64 + key) * INW + ch * 8);
;       *(uint4*)(sK + key * 128 + ((ch ^ (key & 15)) << 3)) = kv;
;       uint4 vv = *(const uint4*)(Vb + (long)(kb * 64 + key) * INW + ch * 8);
;       *(uint4*)((char*)sVt + wt_off(key, ch)) = vv;
;     }
;     __syncthreads();
; #pragma unroll
;     for (int nt = 0; nt < 4; nt++) {
;       f32x4 s0 = f32x4{0.f, 0.f, 0.f, 0.f}, s1 = f32x4{0.f, 0.f, 0.f, 0.f};
;       const int krow = nt * 16 + fr;
; #pragma unroll
;       for (int ks = 0; ks < 4; ks++) {
;         bf16x8 kf = *(const bf16x8*)(sK + krow * 128 + (((ks * 4 + fq) ^ (krow & 15)) << 3));
;         s0 = __builtin_amdgcn_mfma_f32_16x16x32_bf16(kf, qf[0][ks], s0, 0, 0, 0);
;         s1 = __builtin_amdgcn_mfma_f32_16x16x32_bf16(kf, qf[1][ks], s1, 0, 0, 0);
;       }
;       *(f32x4*)(sS + (w * 32 + fr) * 68 + nt * 16 + fq * 4) = s0;
;       *(f32x4*)(sS + (w * 32 + 16 + fr) * 68 + nt * 16 + fq * 4) = s1;
;     }
;     __syncthreads();
;     {
;       float z[32];
;       float* srp = sS + srow * 68 + half * 32;
; #pragma unroll
;       for (int j4 = 0; j4 < 8; j4++) {
;         f32x4 v = *(const f32x4*)(srp + j4 * 4);
;         z[j4 * 4 + 0] = v[0]; z[j4 * 4 + 1] = v[1]; z[j4 * 4 + 2] = v[2]; z[j4 * 4 + 3] = v[3];
;       }
;       const int kbase = kb * 64 + half * 32;
;       float tot = 0.f;
; #pragma unroll
;       for (int j4 = 0; j4 < 8; j4++) {
;         f32x4 sv;
; #pragma unroll
;         for (int e = 0; e < 4; e++) {
;           const int j = j4 * 4 + e;
;           bool valid = (kbase + j) < qg;
;           float zz = z[j];
;           float s = valid ? (fmaxf(zz, 0.f) + __logf(1.f + __expf(-fabsf(zz)))) : 0.f;
.LBB0_274:
	v_add_u32_e32 v66, s93, v186
	v_add_u32_e32 v74, s93, v185
	v_add_u32_e32 v82, s93, v184
	v_mad_u64_u32 v[64:65], s[0:1], v66, s97, v[148:149]
	v_mad_u64_u32 v[68:69], s[0:1], v66, s97, v[150:151]
	v_mad_u64_u32 v[72:73], s[0:1], v74, s97, v[148:149]
	v_mad_u64_u32 v[76:77], s[0:1], v74, s97, v[150:151]
	v_mad_u64_u32 v[80:81], s[0:1], v82, s97, v[148:149]
	v_mad_u64_u32 v[84:85], s[0:1], v82, s97, v[150:151]
	global_load_dwordx4 v[64:67], v[64:65], off
	s_nop 0
	global_load_dwordx4 v[68:71], v[68:69], off
	s_nop 0
	global_load_dwordx4 v[72:75], v[72:73], off
	s_nop 0
	global_load_dwordx4 v[76:79], v[76:77], off
	s_nop 0
	global_load_dwordx4 v[80:83], v[80:81], off
	s_nop 0
	global_load_dwordx4 v[84:87], v[84:85], off
	v_add_u32_e32 v90, s93, v183
	v_mad_u64_u32 v[88:89], s[0:1], v90, s97, v[148:149]
	v_mad_u64_u32 v[92:93], s[0:1], v90, s97, v[150:151]
	global_load_dwordx4 v[88:91], v[88:89], off
	s_nop 0
	global_load_dwordx4 v[92:95], v[92:93], off
	s_nop 0
	global_load_dwordx4 v[96:99], v[152:153], off
	global_load_dwordx4 v[100:103], v[154:155], off
	global_load_dwordx4 v[104:107], v[152:153], off offset:64
	global_load_dwordx4 v[108:111], v[154:155], off offset:64
	global_load_dwordx4 v[112:115], v[152:153], off offset:128
	global_load_dwordx4 v[116:119], v[152:153], off offset:192
	global_load_dwordx4 v[120:123], v[154:155], off offset:128
	global_load_dwordx4 v[124:127], v[154:155], off offset:192
	s_waitcnt vmcnt(15)
	ds_write_b128 v179, v[64:67]
	s_waitcnt vmcnt(14)
	ds_write_b128 v187, v[68:71] offset:16384
	s_waitcnt vmcnt(13)
	ds_write_b128 v180, v[72:75]
	s_waitcnt vmcnt(12)
	ds_write_b128 v188, v[76:79] offset:16384
	s_waitcnt vmcnt(11)
	ds_write_b128 v181, v[80:83]
	s_waitcnt vmcnt(10)
	ds_write_b128 v189, v[84:87] offset:16384
	s_waitcnt vmcnt(9)
	ds_write_b128 v182, v[88:91]
	s_waitcnt vmcnt(8)
	ds_write_b128 v190, v[92:95] offset:16384
	s_waitcnt lgkmcnt(0)
	s_barrier
	ds_read_b128 v[64:67], v191
	ds_read_b128 v[68:71], v191 offset:4096
	ds_read_b128 v[80:83], v191 offset:8192
	ds_read_b128 v[84:87], v191 offset:12288
	s_waitcnt vmcnt(7) lgkmcnt(3)
	v_mfma_f32_16x16x32_bf16 v[72:75], v[64:67], v[96:99], 0
	s_waitcnt vmcnt(6)
	v_mfma_f32_16x16x32_bf16 v[64:67], v[64:67], v[100:103], 0
	s_waitcnt lgkmcnt(2)
	v_mfma_f32_16x16x32_bf16 v[76:79], v[68:71], v[96:99], 0
	v_mfma_f32_16x16x32_bf16 v[68:71], v[68:71], v[100:103], 0
	s_waitcnt lgkmcnt(1)
	v_mfma_f32_16x16x32_bf16 v[88:91], v[80:83], v[96:99], 0
	v_mfma_f32_16x16x32_bf16 v[80:83], v[80:83], v[100:103], 0
	s_waitcnt lgkmcnt(0)
	v_mfma_f32_16x16x32_bf16 v[92:95], v[84:87], v[96:99], 0
	v_mfma_f32_16x16x32_bf16 v[84:87], v[84:87], v[100:103], 0
	ds_read_b128 v[96:99], v192
	ds_read_b128 v[100:103], v192 offset:4096
	s_waitcnt vmcnt(5) lgkmcnt(1)
	v_mfma_f32_16x16x32_bf16 v[72:75], v[96:99], v[104:107], v[72:75]
	s_waitcnt vmcnt(4)
	v_mfma_f32_16x16x32_bf16 v[64:67], v[96:99], v[108:111], v[64:67]
	s_waitcnt lgkmcnt(0)
	v_mfma_f32_16x16x32_bf16 v[76:79], v[100:103], v[104:107], v[76:79]
	v_mfma_f32_16x16x32_bf16 v[68:71], v[100:103], v[108:111], v[68:71]
	ds_read_b128 v[96:99], v192 offset:8192
	ds_read_b128 v[100:103], v192 offset:12288
	s_waitcnt lgkmcnt(1)
	v_mfma_f32_16x16x32_bf16 v[88:91], v[96:99], v[104:107], v[88:91]
	v_mfma_f32_16x16x32_bf16 v[80:83], v[96:99], v[108:111], v[80:83]
	ds_read_b128 v[96:99], v193
	ds_read_b128 v[218:221], v193 offset:4096
	s_waitcnt vmcnt(3) lgkmcnt(1)
	v_mfma_f32_16x16x32_bf16 v[72:75], v[96:99], v[112:115], v[72:75]
	s_waitcnt vmcnt(1)
	v_mfma_f32_16x16x32_bf16 v[64:67], v[96:99], v[120:123], v[64:67]
	s_waitcnt lgkmcnt(0)
	v_mfma_f32_16x16x32_bf16 v[76:79], v[218:221], v[112:115], v[76:79]
	v_mfma_f32_16x16x32_bf16 v[68:71], v[218:221], v[120:123], v[68:71]
	ds_read_b128 v[96:99], v193 offset:8192
	ds_read_b128 v[218:221], v193 offset:12288
	s_waitcnt lgkmcnt(1)
	v_mfma_f32_16x16x32_bf16 v[88:91], v[96:99], v[112:115], v[88:91]
	v_mfma_f32_16x16x32_bf16 v[80:83], v[96:99], v[120:123], v[80:83]
	ds_read_b128 v[96:99], v194
	ds_read_b128 v[222:225], v194 offset:4096
	v_mfma_f32_16x16x32_bf16 v[92:95], v[100:103], v[104:107], v[92:95]
	s_waitcnt lgkmcnt(1)
	v_mfma_f32_16x16x32_bf16 v[72:75], v[96:99], v[116:119], v[72:75]
	s_waitcnt vmcnt(0)
	v_mfma_f32_16x16x32_bf16 v[64:67], v[96:99], v[124:127], v[64:67]
	s_waitcnt lgkmcnt(0)
	v_mfma_f32_16x16x32_bf16 v[76:79], v[222:225], v[116:119], v[76:79]
	v_mfma_f32_16x16x32_bf16 v[68:71], v[222:225], v[124:127], v[68:71]
	ds_read_b128 v[96:99], v194 offset:8192
	ds_read_b128 v[222:225], v194 offset:12288
	s_nop 0
	ds_write_b128 v158, v[72:75] offset:32768
	s_nop 0
	ds_write_b128 v158, v[64:67] offset:37120
	s_nop 0
	ds_write_b128 v158, v[76:79] offset:32832
	ds_write_b128 v158, v[68:71] offset:37184
	v_mfma_f32_16x16x32_bf16 v[84:87], v[100:103], v[108:111], v[84:87]
	v_mfma_f32_16x16x32_bf16 v[92:95], v[218:221], v[112:115], v[92:95]
	s_waitcnt lgkmcnt(5)
	v_mfma_f32_16x16x32_bf16 v[88:91], v[96:99], v[116:119], v[88:91]
	v_mfma_f32_16x16x32_bf16 v[72:75], v[218:221], v[120:123], v[84:87]
	v_mfma_f32_16x16x32_bf16 v[80:83], v[96:99], v[124:127], v[80:83]
	s_waitcnt lgkmcnt(4)
	v_mfma_f32_16x16x32_bf16 v[64:67], v[222:225], v[116:119], v[92:95]
	s_nop 3
	ds_write_b128 v158, v[88:91] offset:32896
	s_nop 0
	ds_write_b128 v158, v[80:83] offset:37248
	s_nop 0
	ds_write_b128 v158, v[64:67] offset:32960
	v_mfma_f32_16x16x32_bf16 v[64:67], v[222:225], v[124:127], v[72:75]
	v_add_u32_e32 v127, s93, v159
	s_nop 6
	ds_write_b128 v158, v[64:67] offset:37312
	s_waitcnt lgkmcnt(0)
	s_barrier
	ds_read_b128 v[72:75], v160 offset:32768
	ds_read_b128 v[80:83], v160 offset:32784
	ds_read_b128 v[84:87], v160 offset:32800
	ds_read_b128 v[88:91], v160 offset:32816
	ds_read_b128 v[92:95], v160 offset:32832
	ds_read_b128 v[96:99], v160 offset:32848
	ds_read_b128 v[100:103], v160 offset:32864
	ds_read_b128 v[76:79], v160 offset:32880
	v_add_u32_e32 v64, 0x1fc0, v127
	v_cmp_lt_i32_e32 vcc, v64, v138
	v_mov_b32_e32 v66, 0
	v_mov_b32_e32 v64, 0
	s_and_saveexec_b64 s[10:11], vcc
	s_cbranch_execz .LBB0_276
	s_waitcnt lgkmcnt(7)
	v_mul_f32_e64 v64, |v72|, s33
	v_exp_f32_e32 v64, v64
	s_nop 0
	v_add_f32_e32 v64, 1.0, v64
	v_log_f32_e32 v64, v64
	v_max_f32_e32 v65, v72, v72
	v_max_f32_e32 v65, 0, v65
	v_mul_f32_e32 v67, 0x3f317217, v64
	v_fma_f32 v67, v64, s3, -v67
	v_fmac_f32_e32 v67, 0x3377d1cf, v64
	v_fmac_f32_e32 v67, 0x3f317217, v64
	v_add_f32_e32 v64, v65, v67
; __device__ void attn_item(const Params& p, int h, int qt, u16* smem) {
;     ...
;           bool valid = (kbase + j) < qg;
;           float zz = z[j];
;           float s = valid ? (fmaxf(zz, 0.f) + __logf(1.f + __expf(-fabsf(zz)))) : 0.f;
;           sv[e] = s;
;           tot += s;
;           z[j] = zz - s;
;         }
;         *(f32x4*)(srp + j4 * 4) = sv;
.LBB0_276:
	s_or_b64 exec, exec, s[10:11]
	v_add_u32_e32 v65, 0x1fc1, v127
	v_cmp_lt_i32_e64 s[8:9], v65, v138
	v_mov_b32_e32 v65, 0
	s_and_saveexec_b64 s[12:13], s[8:9]
	s_cbranch_execz .LBB0_278
	s_waitcnt lgkmcnt(7)
	v_mul_f32_e64 v65, |v73|, s33
	v_exp_f32_e32 v65, v65
	s_nop 0
	v_add_f32_e32 v65, 1.0, v65
	v_log_f32_e32 v65, v65
	v_max_f32_e32 v67, v73, v73
	v_max_f32_e32 v67, 0, v67
	v_mul_f32_e32 v68, 0x3f317217, v65
	v_fma_f32 v68, v65, s3, -v68
	v_fmac_f32_e32 v68, 0x3377d1cf, v65
	v_fmac_f32_e32 v68, 0x3f317217, v65
	v_add_f32_e32 v65, v67, v68
.LBB0_278:
	s_or_b64 exec, exec, s[12:13]
	v_add_u32_e32 v67, 0x1fc2, v127
	v_cmp_lt_i32_e64 s[10:11], v67, v138
	s_and_saveexec_b64 s[14:15], s[10:11]
	s_cbranch_execz .LBB0_280
	s_waitcnt lgkmcnt(7)
	v_mul_f32_e64 v66, |v74|, s33
	v_exp_f32_e32 v66, v66
	s_nop 0
	v_add_f32_e32 v66, 1.0, v66
	v_log_f32_e32 v66, v66
	v_max_f32_e32 v67, v74, v74
	v_max_f32_e32 v67, 0, v67
	v_mul_f32_e32 v68, 0x3f317217, v66
	v_fma_f32 v68, v66, s3, -v68
	v_fmac_f32_e32 v68, 0x3377d1cf, v66
	v_fmac_f32_e32 v68, 0x3f317217, v66
	v_add_f32_e32 v66, v67, v68
.LBB0_280:
	s_or_b64 exec, exec, s[14:15]
	v_add_u32_e32 v67, 0x1fc3, v127
	v_cmp_lt_i32_e64 s[12:13], v67, v138
	v_mov_b32_e32 v68, 0
	v_mov_b32_e32 v67, 0
	s_and_saveexec_b64 s[16:17], s[12:13]
	s_cbranch_execz .LBB0_282
	s_waitcnt lgkmcnt(7)
	v_mul_f32_e64 v67, |v75|, s33
	v_exp_f32_e32 v67, v67
	s_nop 0
	v_add_f32_e32 v67, 1.0, v67
	v_log_f32_e32 v67, v67
	v_max_f32_e32 v69, v75, v75
	v_max_f32_e32 v69, 0, v69
	v_mul_f32_e32 v70, 0x3f317217, v67
	v_fma_f32 v70, v67, s3, -v70
	v_fmac_f32_e32 v70, 0x3377d1cf, v67
	v_fmac_f32_e32 v70, 0x3f317217, v67
	v_add_f32_e32 v67, v69, v70
.LBB0_282:
	s_or_b64 exec, exec, s[16:17]
	v_add_u32_e32 v69, 0x1fc4, v127
	v_cmp_lt_i32_e64 s[14:15], v69, v138
	ds_write_b128 v160, v[64:67] offset:32768
	s_and_saveexec_b64 s[18:19], s[14:15]
	s_cbranch_execz .LBB0_284
	s_waitcnt lgkmcnt(7)
	v_mul_f32_e64 v68, |v80|, s33
	v_exp_f32_e32 v68, v68
	s_nop 0
	v_add_f32_e32 v68, 1.0, v68
	v_log_f32_e32 v68, v68
	v_max_f32_e32 v69, v80, v80
	v_max_f32_e32 v69, 0, v69
	v_mul_f32_e32 v70, 0x3f317217, v68
	v_fma_f32 v70, v68, s3, -v70
	v_fmac_f32_e32 v70, 0x3377d1cf, v68
	v_fmac_f32_e32 v70, 0x3f317217, v68
	v_add_f32_e32 v68, v69, v70
.LBB0_284:
	s_or_b64 exec, exec, s[18:19]
	v_add_u32_e32 v69, 0x1fc5, v127
	v_cmp_lt_i32_e64 s[16:17], v69, v138
	v_mov_b32_e32 v70, 0
	v_mov_b32_e32 v69, 0
	s_and_saveexec_b64 s[20:21], s[16:17]
	s_cbranch_execz .LBB0_286
	s_waitcnt lgkmcnt(7)
	v_mul_f32_e64 v69, |v81|, s33
	v_exp_f32_e32 v69, v69
	s_nop 0
	v_add_f32_e32 v69, 1.0, v69
	v_log_f32_e32 v69, v69
	v_max_f32_e32 v71, v81, v81
	v_max_f32_e32 v71, 0, v71
	v_mul_f32_e32 v104, 0x3f317217, v69
	v_fma_f32 v104, v69, s3, -v104
	v_fmac_f32_e32 v104, 0x3377d1cf, v69
	v_fmac_f32_e32 v104, 0x3f317217, v69
	v_add_f32_e32 v69, v71, v104
.LBB0_286:
	s_or_b64 exec, exec, s[20:21]
	v_add_u32_e32 v71, 0x1fc6, v127
	v_cmp_lt_i32_e64 s[18:19], v71, v138
	s_and_saveexec_b64 s[22:23], s[18:19]
	s_cbranch_execz .LBB0_288
	s_waitcnt lgkmcnt(7)
	v_mul_f32_e64 v70, |v82|, s33
	v_exp_f32_e32 v70, v70
	s_nop 0
	v_add_f32_e32 v70, 1.0, v70
	v_log_f32_e32 v70, v70
	v_max_f32_e32 v71, v82, v82
	v_max_f32_e32 v71, 0, v71
	v_mul_f32_e32 v104, 0x3f317217, v70
	v_fma_f32 v104, v70, s3, -v104
	v_fmac_f32_e32 v104, 0x3377d1cf, v70
	v_fmac_f32_e32 v104, 0x3f317217, v70
	v_add_f32_e32 v70, v71, v104
.LBB0_288:
	s_or_b64 exec, exec, s[22:23]
	v_add_u32_e32 v71, 0x1fc7, v127
	v_cmp_lt_i32_e64 s[20:21], v71, v138
	v_mov_b32_e32 v104, 0
	v_mov_b32_e32 v71, 0
	s_and_saveexec_b64 s[24:25], s[20:21]
	s_cbranch_execz .LBB0_290
	s_waitcnt lgkmcnt(7)
	v_mul_f32_e64 v71, |v83|, s33
	v_exp_f32_e32 v71, v71
	s_nop 0
	v_add_f32_e32 v71, 1.0, v71
	v_log_f32_e32 v71, v71
	v_max_f32_e32 v105, v83, v83
	v_max_f32_e32 v105, 0, v105
	v_mul_f32_e32 v106, 0x3f317217, v71
	v_fma_f32 v106, v71, s3, -v106
	v_fmac_f32_e32 v106, 0x3377d1cf, v71
	v_fmac_f32_e32 v106, 0x3f317217, v71
	v_add_f32_e32 v71, v105, v106
.LBB0_290:
	s_or_b64 exec, exec, s[24:25]
	v_add_u32_e32 v105, 0x1fc8, v127
	v_cmp_lt_i32_e64 s[22:23], v105, v138
	ds_write_b128 v160, v[68:71] offset:32784
	s_and_saveexec_b64 s[26:27], s[22:23]
	s_cbranch_execz .LBB0_292
	s_waitcnt lgkmcnt(7)
	v_mul_f32_e64 v104, |v84|, s33
	v_exp_f32_e32 v104, v104
	s_nop 0
	v_add_f32_e32 v104, 1.0, v104
	v_log_f32_e32 v104, v104
	v_max_f32_e32 v105, v84, v84
	v_max_f32_e32 v105, 0, v105
	v_mul_f32_e32 v106, 0x3f317217, v104
	v_fma_f32 v106, v104, s3, -v106
	v_fmac_f32_e32 v106, 0x3377d1cf, v104
	v_fmac_f32_e32 v106, 0x3f317217, v104
	v_add_f32_e32 v104, v105, v106
.LBB0_292:
	s_or_b64 exec, exec, s[26:27]
	v_add_u32_e32 v105, 0x1fc9, v127
	v_cmp_lt_i32_e64 s[24:25], v105, v138
	v_mov_b32_e32 v106, 0
	v_mov_b32_e32 v105, 0
	s_and_saveexec_b64 s[28:29], s[24:25]
	s_cbranch_execz .LBB0_294
	s_waitcnt lgkmcnt(7)
	v_mul_f32_e64 v105, |v85|, s33
	v_exp_f32_e32 v105, v105
	s_nop 0
	v_add_f32_e32 v105, 1.0, v105
	v_log_f32_e32 v105, v105
	v_max_f32_e32 v107, v85, v85
	v_max_f32_e32 v107, 0, v107
	v_mul_f32_e32 v108, 0x3f317217, v105
	v_fma_f32 v108, v105, s3, -v108
	v_fmac_f32_e32 v108, 0x3377d1cf, v105
	v_fmac_f32_e32 v108, 0x3f317217, v105
	v_add_f32_e32 v105, v107, v108
.LBB0_294:
	s_or_b64 exec, exec, s[28:29]
	v_add_u32_e32 v107, 0x1fca, v127
	v_cmp_lt_i32_e64 s[26:27], v107, v138
	s_and_saveexec_b64 s[30:31], s[26:27]
	s_cbranch_execz .LBB0_296
	s_waitcnt lgkmcnt(7)
	v_mul_f32_e64 v106, |v86|, s33
	v_exp_f32_e32 v106, v106
	s_nop 0
	v_add_f32_e32 v106, 1.0, v106
	v_log_f32_e32 v106, v106
	v_max_f32_e32 v107, v86, v86
	v_max_f32_e32 v107, 0, v107
	v_mul_f32_e32 v108, 0x3f317217, v106
	v_fma_f32 v108, v106, s3, -v108
	v_fmac_f32_e32 v108, 0x3377d1cf, v106
	v_fmac_f32_e32 v108, 0x3f317217, v106
	v_add_f32_e32 v106, v107, v108
; __device__ void attn_item(const Params& p, int h, int qt, u16* smem) {
;     ...
;           bool valid = (kbase + j) < qg;
;           float zz = z[j];
;           float s = valid ? (fmaxf(zz, 0.f) + __logf(1.f + __expf(-fabsf(zz)))) : 0.f;
;           sv[e] = s;
;           tot += s;
;           z[j] = zz - s;
;         }
;         *(f32x4*)(srp + j4 * 4) = sv;
.LBB0_296:
	s_or_b64 exec, exec, s[30:31]
	v_add_u32_e32 v107, 0x1fcb, v127
	v_cmp_lt_i32_e64 s[28:29], v107, v138
	v_mov_b32_e32 v108, 0
	v_mov_b32_e32 v107, 0
	s_and_saveexec_b64 s[34:35], s[28:29]
	s_cbranch_execz .LBB0_298
	s_waitcnt lgkmcnt(7)
	v_mul_f32_e64 v107, |v87|, s33
	v_exp_f32_e32 v107, v107
	s_nop 0
	v_add_f32_e32 v107, 1.0, v107
	v_log_f32_e32 v107, v107
	v_max_f32_e32 v109, v87, v87
	v_max_f32_e32 v109, 0, v109
	v_mul_f32_e32 v110, 0x3f317217, v107
	v_fma_f32 v110, v107, s3, -v110
	v_fmac_f32_e32 v110, 0x3377d1cf, v107
	v_fmac_f32_e32 v110, 0x3f317217, v107
	v_add_f32_e32 v107, v109, v110
.LBB0_298:
	s_or_b64 exec, exec, s[34:35]
	v_add_u32_e32 v109, 0x1fcc, v127
	v_cmp_lt_i32_e64 s[30:31], v109, v138
	ds_write_b128 v160, v[104:107] offset:32800
	s_and_saveexec_b64 s[36:37], s[30:31]
	s_cbranch_execz .LBB0_300
	s_waitcnt lgkmcnt(7)
	v_mul_f32_e64 v108, |v88|, s33
	v_exp_f32_e32 v108, v108
	s_nop 0
	v_add_f32_e32 v108, 1.0, v108
	v_log_f32_e32 v108, v108
	v_max_f32_e32 v109, v88, v88
	v_max_f32_e32 v109, 0, v109
	v_mul_f32_e32 v110, 0x3f317217, v108
	v_fma_f32 v110, v108, s3, -v110
	v_fmac_f32_e32 v110, 0x3377d1cf, v108
	v_fmac_f32_e32 v110, 0x3f317217, v108
	v_add_f32_e32 v108, v109, v110
.LBB0_300:
	s_or_b64 exec, exec, s[36:37]
	v_add_u32_e32 v109, 0x1fcd, v127
	v_cmp_lt_i32_e64 s[34:35], v109, v138
	v_mov_b32_e32 v110, 0
	v_mov_b32_e32 v109, 0
	s_and_saveexec_b64 s[38:39], s[34:35]
	s_cbranch_execz .LBB0_302
	s_waitcnt lgkmcnt(7)
	v_mul_f32_e64 v109, |v89|, s33
	v_exp_f32_e32 v109, v109
	s_nop 0
	v_add_f32_e32 v109, 1.0, v109
	v_log_f32_e32 v109, v109
	v_max_f32_e32 v111, v89, v89
	v_max_f32_e32 v111, 0, v111
	v_mul_f32_e32 v112, 0x3f317217, v109
	v_fma_f32 v112, v109, s3, -v112
	v_fmac_f32_e32 v112, 0x3377d1cf, v109
	v_fmac_f32_e32 v112, 0x3f317217, v109
	v_add_f32_e32 v109, v111, v112
.LBB0_302:
	s_or_b64 exec, exec, s[38:39]
	v_add_u32_e32 v111, 0x1fce, v127
	v_cmp_lt_i32_e64 s[36:37], v111, v138
	s_and_saveexec_b64 s[40:41], s[36:37]
	s_cbranch_execz .LBB0_304
	s_waitcnt lgkmcnt(7)
	v_mul_f32_e64 v110, |v90|, s33
	v_exp_f32_e32 v110, v110
	s_nop 0
	v_add_f32_e32 v110, 1.0, v110
	v_log_f32_e32 v110, v110
	v_max_f32_e32 v111, v90, v90
	v_max_f32_e32 v111, 0, v111
	v_mul_f32_e32 v112, 0x3f317217, v110
	v_fma_f32 v112, v110, s3, -v112
	v_fmac_f32_e32 v112, 0x3377d1cf, v110
	v_fmac_f32_e32 v112, 0x3f317217, v110
	v_add_f32_e32 v110, v111, v112
.LBB0_304:
	s_or_b64 exec, exec, s[40:41]
	v_add_u32_e32 v111, 0x1fcf, v127
	v_cmp_lt_i32_e64 s[38:39], v111, v138
	v_mov_b32_e32 v112, 0
	v_mov_b32_e32 v111, 0
	s_and_saveexec_b64 s[42:43], s[38:39]
	s_cbranch_execz .LBB0_306
	s_waitcnt lgkmcnt(7)
	v_mul_f32_e64 v111, |v91|, s33
	v_exp_f32_e32 v111, v111
	s_nop 0
	v_add_f32_e32 v111, 1.0, v111
	v_log_f32_e32 v111, v111
	v_max_f32_e32 v113, v91, v91
	v_max_f32_e32 v113, 0, v113
	v_mul_f32_e32 v114, 0x3f317217, v111
	v_fma_f32 v114, v111, s3, -v114
	v_fmac_f32_e32 v114, 0x3377d1cf, v111
	v_fmac_f32_e32 v114, 0x3f317217, v111
	v_add_f32_e32 v111, v113, v114
.LBB0_306:
	s_or_b64 exec, exec, s[42:43]
	v_add_u32_e32 v113, 0x1fd0, v127
	v_cmp_lt_i32_e64 s[40:41], v113, v138
	ds_write_b128 v160, v[108:111] offset:32816
	s_and_saveexec_b64 s[44:45], s[40:41]
	s_cbranch_execz .LBB0_308
	s_waitcnt lgkmcnt(7)
	v_mul_f32_e64 v112, |v92|, s33
	v_exp_f32_e32 v112, v112
	s_nop 0
	v_add_f32_e32 v112, 1.0, v112
	v_log_f32_e32 v112, v112
	v_max_f32_e32 v113, v92, v92
	v_max_f32_e32 v113, 0, v113
	v_mul_f32_e32 v114, 0x3f317217, v112
	v_fma_f32 v114, v112, s3, -v114
	v_fmac_f32_e32 v114, 0x3377d1cf, v112
	v_fmac_f32_e32 v114, 0x3f317217, v112
	v_add_f32_e32 v112, v113, v114
.LBB0_308:
	s_or_b64 exec, exec, s[44:45]
	v_add_u32_e32 v113, 0x1fd1, v127
	v_cmp_lt_i32_e64 s[42:43], v113, v138
	v_mov_b32_e32 v114, 0
	v_mov_b32_e32 v113, 0
	s_and_saveexec_b64 s[46:47], s[42:43]
	s_cbranch_execz .LBB0_310
	s_waitcnt lgkmcnt(7)
	v_mul_f32_e64 v113, |v93|, s33
	v_exp_f32_e32 v113, v113
	s_nop 0
	v_add_f32_e32 v113, 1.0, v113
	v_log_f32_e32 v113, v113
	v_max_f32_e32 v115, v93, v93
	v_max_f32_e32 v115, 0, v115
	v_mul_f32_e32 v116, 0x3f317217, v113
	v_fma_f32 v116, v113, s3, -v116
	v_fmac_f32_e32 v116, 0x3377d1cf, v113
	v_fmac_f32_e32 v116, 0x3f317217, v113
	v_add_f32_e32 v113, v115, v116
.LBB0_310:
	s_or_b64 exec, exec, s[46:47]
	v_add_u32_e32 v115, 0x1fd2, v127
	v_cmp_lt_i32_e64 s[44:45], v115, v138
	s_and_saveexec_b64 s[48:49], s[44:45]
	s_cbranch_execz .LBB0_312
	s_waitcnt lgkmcnt(7)
	v_mul_f32_e64 v114, |v94|, s33
	v_exp_f32_e32 v114, v114
	s_nop 0
	v_add_f32_e32 v114, 1.0, v114
	v_log_f32_e32 v114, v114
	v_max_f32_e32 v115, v94, v94
	v_max_f32_e32 v115, 0, v115
	v_mul_f32_e32 v116, 0x3f317217, v114
	v_fma_f32 v116, v114, s3, -v116
	v_fmac_f32_e32 v116, 0x3377d1cf, v114
	v_fmac_f32_e32 v116, 0x3f317217, v114
	v_add_f32_e32 v114, v115, v116
.LBB0_312:
	s_or_b64 exec, exec, s[48:49]
	v_add_u32_e32 v115, 0x1fd3, v127
	v_cmp_lt_i32_e64 s[46:47], v115, v138
	v_mov_b32_e32 v116, 0
	v_mov_b32_e32 v115, 0
	s_and_saveexec_b64 s[50:51], s[46:47]
	s_cbranch_execz .LBB0_314
	s_waitcnt lgkmcnt(7)
	v_mul_f32_e64 v115, |v95|, s33
	v_exp_f32_e32 v115, v115
	s_nop 0
	v_add_f32_e32 v115, 1.0, v115
	v_log_f32_e32 v115, v115
	v_max_f32_e32 v117, v95, v95
	v_max_f32_e32 v117, 0, v117
	v_mul_f32_e32 v118, 0x3f317217, v115
	v_fma_f32 v118, v115, s3, -v118
	v_fmac_f32_e32 v118, 0x3377d1cf, v115
	v_fmac_f32_e32 v118, 0x3f317217, v115
	v_add_f32_e32 v115, v117, v118
; __device__ void attn_item(const Params& p, int h, int qt, u16* smem) {
;     ...
;           bool valid = (kbase + j) < qg;
;           float zz = z[j];
;           float s = valid ? (fmaxf(zz, 0.f) + __logf(1.f + __expf(-fabsf(zz)))) : 0.f;
;           sv[e] = s;
;           tot += s;
;           z[j] = zz - s;
;         }
;         *(f32x4*)(srp + j4 * 4) = sv;
.LBB0_314:
	s_or_b64 exec, exec, s[50:51]
	v_add_u32_e32 v117, 0x1fd4, v127
	v_cmp_lt_i32_e64 s[48:49], v117, v138
	ds_write_b128 v160, v[112:115] offset:32832
	s_and_saveexec_b64 s[52:53], s[48:49]
	s_cbranch_execz .LBB0_316
	s_waitcnt lgkmcnt(7)
	v_mul_f32_e64 v116, |v96|, s33
	v_exp_f32_e32 v116, v116
	s_nop 0
	v_add_f32_e32 v116, 1.0, v116
	v_log_f32_e32 v116, v116
	v_max_f32_e32 v117, v96, v96
	v_max_f32_e32 v117, 0, v117
	v_mul_f32_e32 v118, 0x3f317217, v116
	v_fma_f32 v118, v116, s3, -v118
	v_fmac_f32_e32 v118, 0x3377d1cf, v116
	v_fmac_f32_e32 v118, 0x3f317217, v116
	v_add_f32_e32 v116, v117, v118
.LBB0_316:
	s_or_b64 exec, exec, s[52:53]
	v_add_u32_e32 v117, 0x1fd5, v127
	v_cmp_lt_i32_e64 s[50:51], v117, v138
	v_mov_b32_e32 v118, 0
	v_mov_b32_e32 v117, 0
	s_and_saveexec_b64 s[54:55], s[50:51]
	s_cbranch_execz .LBB0_318
	s_waitcnt lgkmcnt(7)
	v_mul_f32_e64 v117, |v97|, s33
	v_exp_f32_e32 v117, v117
	s_nop 0
	v_add_f32_e32 v117, 1.0, v117
	v_log_f32_e32 v117, v117
	v_max_f32_e32 v119, v97, v97
	v_max_f32_e32 v119, 0, v119
	v_mul_f32_e32 v120, 0x3f317217, v117
	v_fma_f32 v120, v117, s3, -v120
	v_fmac_f32_e32 v120, 0x3377d1cf, v117
	v_fmac_f32_e32 v120, 0x3f317217, v117
	v_add_f32_e32 v117, v119, v120
.LBB0_318:
	s_or_b64 exec, exec, s[54:55]
	v_add_u32_e32 v119, 0x1fd6, v127
	v_cmp_lt_i32_e64 s[52:53], v119, v138
	s_and_saveexec_b64 s[56:57], s[52:53]
	s_cbranch_execz .LBB0_320
	s_waitcnt lgkmcnt(7)
	v_mul_f32_e64 v118, |v98|, s33
	v_exp_f32_e32 v118, v118
	s_nop 0
	v_add_f32_e32 v118, 1.0, v118
	v_log_f32_e32 v118, v118
	v_max_f32_e32 v119, v98, v98
	v_max_f32_e32 v119, 0, v119
	v_mul_f32_e32 v120, 0x3f317217, v118
	v_fma_f32 v120, v118, s3, -v120
	v_fmac_f32_e32 v120, 0x3377d1cf, v118
	v_fmac_f32_e32 v120, 0x3f317217, v118
	v_add_f32_e32 v118, v119, v120
.LBB0_320:
	s_or_b64 exec, exec, s[56:57]
	v_add_u32_e32 v119, 0x1fd7, v127
	v_cmp_lt_i32_e64 s[54:55], v119, v138
	v_mov_b32_e32 v120, 0
	v_mov_b32_e32 v119, 0
	s_and_saveexec_b64 s[58:59], s[54:55]
	s_cbranch_execz .LBB0_322
	s_waitcnt lgkmcnt(7)
	v_mul_f32_e64 v119, |v99|, s33
	v_exp_f32_e32 v119, v119
	s_nop 0
	v_add_f32_e32 v119, 1.0, v119
	v_log_f32_e32 v119, v119
	v_max_f32_e32 v121, v99, v99
	v_max_f32_e32 v121, 0, v121
	v_mul_f32_e32 v122, 0x3f317217, v119
	v_fma_f32 v122, v119, s3, -v122
	v_fmac_f32_e32 v122, 0x3377d1cf, v119
	v_fmac_f32_e32 v122, 0x3f317217, v119
	v_add_f32_e32 v119, v121, v122
.LBB0_322:
	s_or_b64 exec, exec, s[58:59]
	v_add_u32_e32 v121, 0x1fd8, v127
	v_cmp_lt_i32_e64 s[56:57], v121, v138
	ds_write_b128 v160, v[116:119] offset:32848
	s_and_saveexec_b64 s[60:61], s[56:57]
	s_cbranch_execz .LBB0_324
	s_waitcnt lgkmcnt(7)
	v_mul_f32_e64 v120, |v100|, s33
	v_exp_f32_e32 v120, v120
	s_nop 0
	v_add_f32_e32 v120, 1.0, v120
	v_log_f32_e32 v120, v120
	v_max_f32_e32 v121, v100, v100
	v_max_f32_e32 v121, 0, v121
	v_mul_f32_e32 v122, 0x3f317217, v120
	v_fma_f32 v122, v120, s3, -v122
	v_fmac_f32_e32 v122, 0x3377d1cf, v120
	v_fmac_f32_e32 v122, 0x3f317217, v120
	v_add_f32_e32 v120, v121, v122
.LBB0_324:
	s_or_b64 exec, exec, s[60:61]
	v_add_u32_e32 v121, 0x1fd9, v127
	v_cmp_lt_i32_e64 s[58:59], v121, v138
	v_mov_b32_e32 v122, 0
	v_mov_b32_e32 v121, 0
	s_and_saveexec_b64 s[64:65], s[58:59]
	s_cbranch_execz .LBB0_326
	s_waitcnt lgkmcnt(7)
	v_mul_f32_e64 v121, |v101|, s33
	v_exp_f32_e32 v121, v121
	s_nop 0
	v_add_f32_e32 v121, 1.0, v121
	v_log_f32_e32 v121, v121
	v_max_f32_e32 v123, v101, v101
	v_max_f32_e32 v123, 0, v123
	v_mul_f32_e32 v124, 0x3f317217, v121
	v_fma_f32 v124, v121, s3, -v124
	v_fmac_f32_e32 v124, 0x3377d1cf, v121
	v_fmac_f32_e32 v124, 0x3f317217, v121
	v_add_f32_e32 v121, v123, v124
; __device__ void attn_item(const Params& p, int h, int qt, u16* smem) {
;     ...
;           bool valid = (kbase + j) < qg;
;           float zz = z[j];
;           float s = valid ? (fmaxf(zz, 0.f) + __logf(1.f + __expf(-fabsf(zz)))) : 0.f;
;           sv[e] = s;
;           tot += s;
;           z[j] = zz - s;
;         }
;         *(f32x4*)(srp + j4 * 4) = sv;
.LBB0_326:
	s_or_b64 exec, exec, s[64:65]
	v_add_u32_e32 v123, 0x1fda, v127
	v_cmp_lt_i32_e64 s[60:61], v123, v138
	s_and_saveexec_b64 s[66:67], s[60:61]
	s_cbranch_execz .LBB0_328
	s_waitcnt lgkmcnt(7)
	v_mul_f32_e64 v122, |v102|, s33
	v_exp_f32_e32 v122, v122
	s_nop 0
	v_add_f32_e32 v122, 1.0, v122
	v_log_f32_e32 v122, v122
	v_max_f32_e32 v123, v102, v102
	v_max_f32_e32 v123, 0, v123
	v_mul_f32_e32 v124, 0x3f317217, v122
	v_fma_f32 v124, v122, s3, -v124
	v_fmac_f32_e32 v124, 0x3377d1cf, v122
	v_fmac_f32_e32 v124, 0x3f317217, v122
	v_add_f32_e32 v122, v123, v124
.LBB0_328:
	s_or_b64 exec, exec, s[66:67]
	v_add_u32_e32 v123, 0x1fdb, v127
	v_cmp_lt_i32_e64 s[0:1], v123, v138
	v_mov_b32_e32 v124, 0
	v_mov_b32_e32 v123, 0
	s_and_saveexec_b64 s[68:69], s[0:1]
	s_cbranch_execz .LBB0_330
	s_waitcnt lgkmcnt(7)
	v_mul_f32_e64 v123, |v103|, s33
	v_exp_f32_e32 v123, v123
	s_nop 0
	v_add_f32_e32 v123, 1.0, v123
	v_log_f32_e32 v123, v123
	v_max_f32_e32 v125, v103, v103
	v_max_f32_e32 v125, 0, v125
	v_mul_f32_e32 v126, 0x3f317217, v123
	v_fma_f32 v126, v123, s3, -v126
	v_fmac_f32_e32 v126, 0x3377d1cf, v123
	v_fmac_f32_e32 v126, 0x3f317217, v123
	v_add_f32_e32 v123, v125, v126
.LBB0_330:
	s_or_b64 exec, exec, s[68:69]
	v_add_u32_e32 v125, 0x1fdc, v127
	v_cmp_lt_i32_e64 s[64:65], v125, v138
	ds_write_b128 v160, v[120:123] offset:32864
	s_and_saveexec_b64 s[70:71], s[64:65]
	s_cbranch_execz .LBB0_332
	s_waitcnt lgkmcnt(7)
	v_mul_f32_e64 v124, |v76|, s33
	v_exp_f32_e32 v124, v124
	s_nop 0
	v_add_f32_e32 v124, 1.0, v124
	v_log_f32_e32 v124, v124
	v_max_f32_e32 v125, v76, v76
	v_max_f32_e32 v125, 0, v125
	v_mul_f32_e32 v126, 0x3f317217, v124
	v_fma_f32 v126, v124, s3, -v126
	v_fmac_f32_e32 v126, 0x3377d1cf, v124
	v_fmac_f32_e32 v126, 0x3f317217, v124
	v_add_f32_e32 v124, v125, v126
.LBB0_332:
	s_or_b64 exec, exec, s[70:71]
	v_add_u32_e32 v125, 0x1fdd, v127
	v_cmp_lt_i32_e64 s[66:67], v125, v138
	v_mov_b32_e32 v126, 0
	v_mov_b32_e32 v125, 0
	s_and_saveexec_b64 s[72:73], s[66:67]
	s_cbranch_execz .LBB0_334
	s_waitcnt lgkmcnt(7)
	v_mul_f32_e64 v125, |v77|, s33
	v_exp_f32_e32 v125, v125
	s_nop 0
	v_add_f32_e32 v125, 1.0, v125
	v_log_f32_e32 v125, v125
	v_max_f32_e32 v170, v77, v77
	v_max_f32_e32 v170, 0, v170
	v_mul_f32_e32 v171, 0x3f317217, v125
	v_fma_f32 v171, v125, s3, -v171
	v_fmac_f32_e32 v171, 0x3377d1cf, v125
	v_fmac_f32_e32 v171, 0x3f317217, v125
	v_add_f32_e32 v125, v170, v171
.LBB0_334:
	s_or_b64 exec, exec, s[72:73]
	v_add_u32_e32 v170, 0x1fde, v127
	v_cmp_lt_i32_e64 s[68:69], v170, v138
	s_and_saveexec_b64 s[74:75], s[68:69]
	s_cbranch_execz .LBB0_336
	s_waitcnt lgkmcnt(7)
	v_mul_f32_e64 v126, |v78|, s33
	v_exp_f32_e32 v126, v126
	s_nop 0
	v_add_f32_e32 v126, 1.0, v126
	v_log_f32_e32 v126, v126
	v_max_f32_e32 v170, v78, v78
	v_max_f32_e32 v170, 0, v170
	v_mul_f32_e32 v171, 0x3f317217, v126
	v_fma_f32 v171, v126, s3, -v171
	v_fmac_f32_e32 v171, 0x3377d1cf, v126
	v_fmac_f32_e32 v171, 0x3f317217, v126
	v_add_f32_e32 v126, v170, v171
.LBB0_336:
	s_or_b64 exec, exec, s[74:75]
	v_add_u32_e32 v127, 0x1fdf, v127
	v_cmp_lt_i32_e64 s[70:71], v127, v138
	v_mov_b32_e32 v127, 0
	s_and_saveexec_b64 s[78:79], s[70:71]
	s_cbranch_execz .LBB0_338
	s_waitcnt lgkmcnt(7)
	v_mul_f32_e64 v127, |v79|, s33
	v_exp_f32_e32 v127, v127
	s_nop 0
	v_add_f32_e32 v127, 1.0, v127
	v_log_f32_e32 v127, v127
	v_max_f32_e32 v170, v79, v79
	v_max_f32_e32 v170, 0, v170
	v_mul_f32_e32 v171, 0x3f317217, v127
	v_fma_f32 v171, v127, s3, -v171
	v_fmac_f32_e32 v171, 0x3377d1cf, v127
	v_fmac_f32_e32 v171, 0x3f317217, v127
	v_add_f32_e32 v127, v170, v171

; __device__ void gmlp_item(const Params& p, int nb, int g, u16* smem) {
;   const int t = threadIdx.x, lane = t & 63, wid = t >> 6, wr = wid >> 1, wc = wid & 1, fr = lane & 15, fq = lane >> 4;
;   u16* sA = smem;
;   u16* sB = smem + 16384;
; #pragma unroll
;   for (int i = 0; i < 8; i++) {
;     int q = t + 256 * i;
;     int tt = q >> 4, sc = q & 15, kt = sc >> 3, c = sc & 7;
;     const float* src = p.gm_w_s + ((long)g * 128 + tt) * 128 + sc * 8;
;     float4 a = *(const float4*)src, b = *(const float4*)(src + 4);
;     bool keep = (tt >> 6) >= kt;
;     uint4 w;
;     w.x = keep ? pack2(a.x, a.y) : 0u; w.y = keep ? pack2(a.z, a.w) : 0u;
;     w.z = keep ? pack2(b.x, b.y) : 0u; w.w = keep ? pack2(b.z, b.w) : 0u;
;     *(uint4*)(sA + kt * 8192 + tt * 64 + ((c ^ ((tt >> 1) & 7)) << 3)) = w;
;   }
; __device__ void phase_mix(const Params& p, u16* smem) {
;     ...
;   for (int j = blockIdx.x; j < NG; j += gridDim.x) gmlp_item(p, j >> 3, j & 7, smem);
.LBB0_344:
	v_lshrrev_b32_e32 v2, 5, v128
	v_xor_b32_e32 v2, v2, v128
	v_lshrrev_b32_e32 v0, 3, v164
	v_lshlrev_b32_e32 v2, 4, v2
	v_lshlrev_b32_e32 v1, 14, v0
	s_movk_i32 s0, 0x110
	v_and_b32_e32 v2, 0x70, v2
	v_add3_u32 v62, s0, v1, v2
	v_lshlrev_b32_e32 v1, 3, v163
	v_and_b32_e32 v64, 0x3f80, v1
	v_lshrrev_b32_e32 v1, 10, v163
	v_cmp_lt_u32_e64 s[4:5], v1, v0
	v_cmp_ge_u32_e64 s[6:7], v1, v0
	v_lshlrev_b32_e32 v1, 3, v177
	v_and_b32_e32 v65, 0x3f80, v1
	v_lshrrev_b32_e32 v1, 10, v177
	v_cmp_lt_u32_e64 s[8:9], v1, v0
	v_cmp_ge_u32_e64 s[10:11], v1, v0
	v_lshlrev_b32_e32 v1, 3, v178
	v_and_b32_e32 v66, 0x3f80, v1
	v_lshrrev_b32_e32 v1, 10, v178
	v_cmp_lt_u32_e64 s[12:13], v1, v0
	v_cmp_ge_u32_e64 s[14:15], v1, v0
	v_add_u32_e32 v0, 0x2800, v174
	v_and_b32_e32 v69, 0x7f80, v0
	v_add_u32_e32 v0, 0x3000, v174
	v_and_b32_e32 v70, 0x7f80, v0
	v_add_u32_e32 v0, 0x3800, v174
	v_and_b32_e32 v71, 0x7f80, v0
	v_and_b32_e32 v0, 64, v173
	s_movk_i32 s0, 0x380
	v_and_or_b32 v1, v128, s0, v0
	v_and_b32_e32 v2, 56, v135
	v_mov_b32_e32 v3, 0x110
	v_lshl_add_u32 v1, v1, 7, v3
	v_lshlrev_b32_e32 v2, 1, v2
	v_lshlrev_b32_e32 v4, 1, v227
	v_add3_u32 v72, v1, v2, v4
	v_bitop3_b32 v2, v135, 8, 56 bitop3:0x6c
	v_lshlrev_b32_e32 v2, 1, v2
	v_add3_u32 v73, v1, v2, v4
	v_bitop3_b32 v2, v135, 16, 56 bitop3:0x6c
	v_lshlrev_b32_e32 v2, 1, v2
	v_add3_u32 v74, v1, v2, v4
	v_bitop3_b32 v2, v135, 24, 56 bitop3:0x6c
	v_lshlrev_b32_e32 v2, 1, v2
	v_add3_u32 v75, v1, v2, v4
	v_bitop3_b32 v2, v135, 32, 56 bitop3:0x6c
	v_lshlrev_b32_e32 v2, 1, v2
	v_add3_u32 v76, v1, v2, v4
	v_bitop3_b32 v2, v135, 40, 56 bitop3:0x6c
	v_lshlrev_b32_e32 v2, 1, v2
	v_add3_u32 v77, v1, v2, v4
	v_bitop3_b32 v2, v135, 48, 56 bitop3:0x6c
	v_lshlrev_b32_e32 v2, 1, v2
	v_add3_u32 v78, v1, v2, v4
	v_bitop3_b32 v2, v135, 56, v135 bitop3:0xc
	v_lshlrev_b32_e32 v2, 1, v2
	v_add3_u32 v79, v1, v2, v4
	v_lshrrev_b32_e32 v1, 1, v164
	v_xor_b32_e32 v2, v226, v1
	v_mov_b32_e32 v49, 0
	v_lshl_add_u32 v2, v2, 4, v3
	v_lshl_or_b32 v4, v166, 13, v162
	v_lshl_or_b32 v5, v165, 13, v162
	v_xor_b32_e32 v1, v161, v1
	v_lshlrev_b32_e32 v48, 2, v132
	v_and_b32_e32 v67, 0x1f80, v174
	v_add_u32_e32 v80, v2, v4
	v_add_u32_e32 v81, v2, v5
	v_lshl_add_u32 v1, v1, 4, v3
	v_lshl_or_b32 v84, v166, 6, v164
	v_lshl_or_b32 v2, v165, 6, v130
	v_lshl_add_u64 v[50:51], s[86:87], 0, v[48:49]
	v_lshlrev_b32_e32 v48, 2, v0
	s_add_u32 s16, s92, 0x22f00000
	v_readlane_b32 s96, v255, 43
	v_readlane_b32 s94, v255, 47
	v_readlane_b32 s34, v255, 41
	v_lshlrev_b32_e32 v63, 7, v133
	v_cmp_gt_u32_e32 vcc, 8, v164
	v_or_b32_e32 v68, 0x2000, v67
	s_movk_i32 s2, 0x2800
	v_add_u32_e32 v82, v1, v4
	v_add_u32_e32 v83, v1, v5
	v_or_b32_e32 v85, 16, v84
	v_or_b32_e32 v86, 32, v84
	v_or_b32_e32 v87, 48, v84
	v_lshl_add_u64 v[52:53], s[82:83], 0, v[48:49]
	v_lshl_add_u64 v[54:55], s[84:85], 0, v[48:49]
	s_addc_u32 s17, s93, 0
	v_readlane_b32 s97, v255, 44
	s_lshl_b32 s3, s96, 4
	s_lshl_b32 s22, s94, 4
	s_mov_b32 s19, 0
	v_lshlrev_b32_e32 v56, 1, v0
	s_mov_b64 s[20:21], 0x1df00800
	s_mov_b32 s23, 0x1df00000
	v_mov_b32_e32 v88, 0x3727c5ac
	s_mov_b32 s24, 0x800000
	v_lshlrev_b32_e32 v58, 1, v2
	s_mov_b32 s25, s96
	v_readlane_b32 s35, v255, 42
	v_readlane_b32 s95, v255, 48
	s_lshr_b32 m0, s94, 1
	s_cmp_ge_u32 s96, m0
	s_cbranch_scc1 .LBB0_354
	s_branch .LBB0_346
.LBB0_345:
	s_or_b64 exec, exec, s[0:1]
	v_or_b32_e32 v1, s28, v68
	v_lshlrev_b32_e32 v48, 2, v1
	v_lshl_add_u64 v[10:11], v[50:51], 0, v[48:49]
	v_add_lshl_u32 v48, s28, v69, 2
	global_load_dwordx4 v[6:9], v[10:11], off offset:16
	global_load_dwordx4 v[14:17], v[10:11], off
	v_lshl_add_u64 v[10:11], v[50:51], 0, v[48:49]
	v_add_lshl_u32 v48, s28, v70, 2
	global_load_dwordx4 v[18:21], v[10:11], off offset:16
	global_load_dwordx4 v[22:25], v[10:11], off
	v_lshl_add_u64 v[10:11], v[50:51], 0, v[48:49]
	s_and_b32 s26, s3, 0xffffff80
	global_load_dwordx4 v[26:29], v[10:11], off offset:16
	global_load_dwordx4 v[30:33], v[10:11], off
	v_add_u32_e32 v1, s26, v135
	v_mov_b64_e32 v[10:11], s[92:93]
	v_mad_i64_i32 v[10:11], s[0:1], v1, s2, v[10:11]
	s_lshl_b32 s18, s27, 8
	v_lshl_add_u64 v[10:11], v[10:11], 0, s[18:19]
	v_mov_b32_e32 v57, v49
	v_lshl_add_u64 v[10:11], v[10:11], 0, v[56:57]
	v_add_co_u32_e64 v34, s[0:1], s23, v10
	s_waitcnt vmcnt(6)
	v_cvt_pk_bf16_f32 v1, v2, v3
	v_addc_co_u32_e64 v35, s[0:1], 0, v11, s[0:1]
	global_load_dwordx4 v[34:37], v[34:35], off offset:2048
	v_lshl_add_u64 v[10:11], v[10:11], 0, s[20:21]
	global_load_dwordx4 v[38:41], v[10:11], off offset:16
	global_load_dwordx4 v[42:45], v[10:11], off offset:32
	global_load_dwordx4 v[90:93], v[10:11], off offset:48
	global_load_dwordx4 v[138:141], v[10:11], off offset:64
	global_load_dwordx4 v[142:145], v[10:11], off offset:80
	global_load_dwordx4 v[146:149], v[10:11], off offset:96
	global_load_dwordx4 v[150:153], v[10:11], off offset:112
	v_cvt_pk_bf16_f32 v2, v4, v5
	v_cvt_pk_bf16_f32 v3, v12, v13
	v_add_u32_e32 v4, v62, v66
	v_cndmask_b32_e64 v1, v1, 0, s[12:13]
	v_cndmask_b32_e64 v2, v2, 0, s[12:13]
	v_cndmask_b32_e64 v3, v3, 0, s[12:13]
	ds_write_b128 v4, v[0:3]
	v_add_u32_e32 v5, v62, v67
	v_add_u32_e32 v10, v62, v69
	v_add_lshl_u32 v48, s28, v71, 2
	s_lshl_b32 s0, s27, 9
	s_mov_b32 s1, s19
	v_add_u32_e32 v132, v62, v70
	s_waitcnt vmcnt(13)
	v_cvt_pk_bf16_f32 v2, v6, v7
	s_waitcnt vmcnt(12)
	v_cvt_pk_bf16_f32 v0, v14, v15
	v_cvt_pk_bf16_f32 v1, v16, v17
	v_cvt_pk_bf16_f32 v3, v8, v9
	ds_write_b128 v5, v[0:3] offset:8192
	s_waitcnt vmcnt(10)
	v_cvt_pk_bf16_f32 v0, v22, v23
	v_cvt_pk_bf16_f32 v1, v24, v25
	v_cvt_pk_bf16_f32 v2, v18, v19
	v_cvt_pk_bf16_f32 v3, v20, v21
	ds_write_b128 v10, v[0:3]
	s_waitcnt vmcnt(9)
; __device__ __forceinline__ float bflo(uint32_t w) { return __uint_as_float(w << 16); }
; __device__ __forceinline__ float bfhi(uint32_t w) { return __uint_as_float(w & 0xffff0000u); }
; __device__ void gmlp_item(const Params& p, int nb, int g, u16* smem) {
;     ...
;     const int s = t >> 1, half = t & 1;
;     const u16* vp = p.proj() + (long)(nb * 128 + s) * INW + 1024 + g * 128 + half * 64;
;     float v[64];
; #pragma unroll
;     for (int i = 0; i < 8; i++) {
;       uint4 w = *(const uint4*)(vp + i * 8);
;       v[i * 8 + 0] = bflo(w.x); v[i * 8 + 1] = bfhi(w.x); v[i * 8 + 2] = bflo(w.y); v[i * 8 + 3] = bfhi(w.y);
;       v[i * 8 + 4] = bflo(w.z); v[i * 8 + 5] = bfhi(w.z); v[i * 8 + 6] = bflo(w.w); v[i * 8 + 7] = bfhi(w.w);
;     }
;     float sum = 0.f;
; #pragma unroll
;     for (int i = 0; i < 64; i++) sum += v[i];
;     sum += __shfl_xor(sum, 1);
	v_cvt_pk_bf16_f32 v3, v28, v29
	v_cvt_pk_bf16_f32 v2, v26, v27
	v_lshl_add_u64 v[8:9], v[50:51], 0, v[48:49]
	s_waitcnt vmcnt(8)
	v_cvt_pk_bf16_f32 v1, v32, v33
	v_lshl_add_u64 v[32:33], v[52:53], 0, s[0:1]
	v_cvt_pk_bf16_f32 v0, v30, v31
	v_lshl_add_u64 v[30:31], v[54:55], 0, s[0:1]
	s_waitcnt vmcnt(6)
	v_lshlrev_b32_e32 v117, 16, v38
	v_and_b32_e32 v116, 0xffff0000, v38
	v_lshlrev_b32_e32 v115, 16, v39
	v_lshlrev_b32_e32 v125, 16, v34
	v_and_b32_e32 v124, 0xffff0000, v34
	v_add_f32_e32 v4, 0, v125
	v_lshlrev_b32_e32 v123, 16, v35
	v_add_f32_e32 v4, v4, v124
	v_and_b32_e32 v122, 0xffff0000, v35
	v_add_f32_e32 v4, v4, v123
	v_lshlrev_b32_e32 v121, 16, v36
	v_add_f32_e32 v4, v4, v122
	v_and_b32_e32 v120, 0xffff0000, v36
	v_add_f32_e32 v4, v4, v121
	v_lshlrev_b32_e32 v119, 16, v37
	v_add_f32_e32 v4, v4, v120
	v_and_b32_e32 v118, 0xffff0000, v37
	v_add_f32_e32 v4, v4, v119
	v_add_f32_e32 v4, v4, v118
	v_add_f32_e32 v4, v4, v117
	v_add_f32_e32 v4, v4, v116
	v_and_b32_e32 v114, 0xffff0000, v39
	v_add_f32_e32 v4, v4, v115
	v_lshlrev_b32_e32 v113, 16, v40
	v_add_f32_e32 v4, v4, v114
	v_and_b32_e32 v112, 0xffff0000, v40
	v_add_f32_e32 v4, v4, v113
	v_lshlrev_b32_e32 v111, 16, v41
	v_add_f32_e32 v4, v4, v112
	v_and_b32_e32 v110, 0xffff0000, v41
	v_add_f32_e32 v4, v4, v111
	s_waitcnt vmcnt(5)
	v_lshlrev_b32_e32 v109, 16, v42
	v_add_f32_e32 v4, v4, v110
	v_and_b32_e32 v108, 0xffff0000, v42
	v_add_f32_e32 v4, v4, v109
	v_lshlrev_b32_e32 v107, 16, v43
	v_add_f32_e32 v4, v4, v108
	v_and_b32_e32 v106, 0xffff0000, v43
	v_add_f32_e32 v4, v4, v107
	v_lshlrev_b32_e32 v105, 16, v44
	v_add_f32_e32 v4, v4, v106
	v_and_b32_e32 v104, 0xffff0000, v44
	v_add_f32_e32 v4, v4, v105
	v_lshlrev_b32_e32 v103, 16, v45
	v_add_f32_e32 v4, v4, v104
	v_and_b32_e32 v102, 0xffff0000, v45
	v_add_f32_e32 v4, v4, v103
	s_waitcnt vmcnt(4)
	v_lshlrev_b32_e32 v101, 16, v90
	v_add_f32_e32 v4, v4, v102
	v_and_b32_e32 v100, 0xffff0000, v90
	v_add_f32_e32 v4, v4, v101
	v_lshlrev_b32_e32 v99, 16, v91
	v_add_f32_e32 v4, v4, v100
	v_and_b32_e32 v98, 0xffff0000, v91
	v_add_f32_e32 v4, v4, v99
	v_lshlrev_b32_e32 v97, 16, v92
	v_add_f32_e32 v4, v4, v98
	v_and_b32_e32 v96, 0xffff0000, v92
	v_add_f32_e32 v4, v4, v97
	v_lshlrev_b32_e32 v95, 16, v93
	v_add_f32_e32 v4, v4, v96
	v_and_b32_e32 v94, 0xffff0000, v93
	v_add_f32_e32 v4, v4, v95
	s_waitcnt vmcnt(3)
	v_lshlrev_b32_e32 v93, 16, v138
	v_add_f32_e32 v4, v4, v94
	v_and_b32_e32 v92, 0xffff0000, v138
	v_add_f32_e32 v4, v4, v93
	v_lshlrev_b32_e32 v91, 16, v139
	v_add_f32_e32 v4, v4, v92
	v_and_b32_e32 v90, 0xffff0000, v139
	v_add_f32_e32 v4, v4, v91
	v_lshlrev_b32_e32 v89, 16, v140
	v_add_f32_e32 v4, v4, v90
	v_and_b32_e32 v61, 0xffff0000, v140
	v_add_f32_e32 v4, v4, v89
	v_lshlrev_b32_e32 v60, 16, v141
	v_add_f32_e32 v4, v4, v61
	v_and_b32_e32 v59, 0xffff0000, v141
	v_add_f32_e32 v4, v4, v60
	s_waitcnt vmcnt(2)
	v_lshlrev_b32_e32 v57, 16, v142
	v_add_f32_e32 v4, v4, v59
	v_and_b32_e32 v47, 0xffff0000, v142
	v_add_f32_e32 v4, v4, v57
	v_lshlrev_b32_e32 v46, 16, v143
	v_add_f32_e32 v4, v4, v47
	v_and_b32_e32 v45, 0xffff0000, v143
	v_add_f32_e32 v4, v4, v46
	v_lshlrev_b32_e32 v44, 16, v144
	v_add_f32_e32 v4, v4, v45
	v_and_b32_e32 v43, 0xffff0000, v144
	v_add_f32_e32 v4, v4, v44
	v_lshlrev_b32_e32 v42, 16, v145
	v_add_f32_e32 v4, v4, v43
	v_and_b32_e32 v41, 0xffff0000, v145
	v_add_f32_e32 v4, v4, v42
	s_waitcnt vmcnt(1)
	v_lshlrev_b32_e32 v40, 16, v146
	v_add_f32_e32 v4, v4, v41
	v_and_b32_e32 v39, 0xffff0000, v146
	v_add_f32_e32 v4, v4, v40
	v_lshlrev_b32_e32 v38, 16, v147
	v_add_f32_e32 v4, v4, v39
	v_and_b32_e32 v37, 0xffff0000, v147
	v_add_f32_e32 v4, v4, v38
	v_lshlrev_b32_e32 v36, 16, v148
	v_add_f32_e32 v4, v4, v37
	v_and_b32_e32 v35, 0xffff0000, v148
	v_add_f32_e32 v4, v4, v36
	v_lshlrev_b32_e32 v29, 16, v149
	v_add_f32_e32 v4, v4, v35
	v_and_b32_e32 v28, 0xffff0000, v149
	v_add_f32_e32 v4, v4, v29
	s_waitcnt vmcnt(0)
	v_lshlrev_b32_e32 v27, 16, v150
	v_add_f32_e32 v4, v4, v28
	v_and_b32_e32 v26, 0xffff0000, v150
	v_add_f32_e32 v4, v4, v27
	v_lshlrev_b32_e32 v25, 16, v151
	v_add_f32_e32 v4, v4, v26
	v_and_b32_e32 v24, 0xffff0000, v151
	v_add_f32_e32 v4, v4, v25
	v_lshlrev_b32_e32 v23, 16, v152
	v_add_f32_e32 v4, v4, v24
	v_and_b32_e32 v22, 0xffff0000, v152
	v_add_f32_e32 v4, v4, v23
	v_lshlrev_b32_e32 v21, 16, v153
	v_add_f32_e32 v4, v4, v22
	v_and_b32_e32 v20, 0xffff0000, v153
	v_add_f32_e32 v4, v4, v21
	v_add_f32_e32 v12, v4, v20
	global_load_dwordx4 v[4:7], v[8:9], off offset:16
	s_nop 0
	global_load_dwordx4 v[8:11], v[8:9], off
	ds_bpermute_b32 v13, v137, v12
	global_load_dwordx4 v[138:141], v[32:33], off offset:16
	global_load_dwordx4 v[142:145], v[32:33], off
	global_load_dwordx4 v[146:149], v[30:31], off offset:16
	global_load_dwordx4 v[150:153], v[30:31], off
	s_waitcnt lgkmcnt(0)
; __device__ __forceinline__ u16 f2bf(float f) { return (u16)(pack2(f, f) & 0xffffu); }
; __device__ void gmlp_item(const Params& p, int nb, int g, u16* smem) {
;     ...
;     const float mean = sum * (1.f / 128.f);
;     float sq = 0.f;
; #pragma unroll
;     for (int i = 0; i < 64; i++) { float d = v[i] - mean; sq += d * d; }
;     sq += __shfl_xor(sq, 1);
;     const float rstd = rsqrtf(sq * (1.f / 128.f) + 1e-5f);
;     const int kt = s >> 6, kk = s & 63;
;     const float* lg = p.gm_ln_g + g * 128 + half * 64;
;     const float* lb = p.gm_ln_b + g * 128 + half * 64;
; #pragma unroll
;     for (int i = 0; i < 64; i++) {
;       int cc = half * 64 + i;
;       float val = (v[i] - mean) * rstd * lg[i] + lb[i];
;       sB[kt * 8192 + cc * 64 + (((kk >> 3) ^ ((cc >> 1) & 7)) << 3) + (kk & 7)] = f2bf(val);
	v_add_f32_e32 v48, v12, v13
	v_fmac_f32_e32 v124, 0xbc000000, v48
	v_fmac_f32_e32 v125, 0xbc000000, v48
	v_mul_f32_e32 v162, v124, v124
	v_fmac_f32_e32 v162, v125, v125
	v_fmac_f32_e32 v123, 0xbc000000, v48
	v_fmac_f32_e32 v162, v123, v123
	v_fmac_f32_e32 v122, 0xbc000000, v48
	v_fmac_f32_e32 v162, v122, v122
	v_fmac_f32_e32 v121, 0xbc000000, v48
	v_fmac_f32_e32 v162, v121, v121
	v_fmac_f32_e32 v120, 0xbc000000, v48
	v_fmac_f32_e32 v162, v120, v120
	v_fmac_f32_e32 v119, 0xbc000000, v48
	v_fmac_f32_e32 v162, v119, v119
	v_fmac_f32_e32 v118, 0xbc000000, v48
	v_fmac_f32_e32 v162, v118, v118
	v_fmac_f32_e32 v117, 0xbc000000, v48
	v_fmac_f32_e32 v162, v117, v117
	v_fmac_f32_e32 v116, 0xbc000000, v48
	v_fmac_f32_e32 v162, v116, v116
	v_fmac_f32_e32 v115, 0xbc000000, v48
	v_fmac_f32_e32 v162, v115, v115
	v_fmac_f32_e32 v114, 0xbc000000, v48
	v_fmac_f32_e32 v162, v114, v114
	v_fmac_f32_e32 v113, 0xbc000000, v48
	v_fmac_f32_e32 v162, v113, v113
	v_fmac_f32_e32 v112, 0xbc000000, v48
	v_fmac_f32_e32 v162, v112, v112
	v_fmac_f32_e32 v111, 0xbc000000, v48
	v_fmac_f32_e32 v162, v111, v111
	v_fmac_f32_e32 v110, 0xbc000000, v48
	v_fmac_f32_e32 v162, v110, v110
	v_fmac_f32_e32 v109, 0xbc000000, v48
	v_fmac_f32_e32 v162, v109, v109
	v_fmac_f32_e32 v108, 0xbc000000, v48
	v_fmac_f32_e32 v162, v108, v108
	v_fmac_f32_e32 v107, 0xbc000000, v48
	v_fmac_f32_e32 v162, v107, v107
	v_fmac_f32_e32 v106, 0xbc000000, v48
	v_fmac_f32_e32 v162, v106, v106
	v_fmac_f32_e32 v105, 0xbc000000, v48
	v_fmac_f32_e32 v162, v105, v105
	v_fmac_f32_e32 v104, 0xbc000000, v48
	v_fmac_f32_e32 v162, v104, v104
	v_fmac_f32_e32 v103, 0xbc000000, v48
	v_fmac_f32_e32 v162, v103, v103
	v_fmac_f32_e32 v102, 0xbc000000, v48
	v_fmac_f32_e32 v162, v102, v102
	v_fmac_f32_e32 v101, 0xbc000000, v48
	v_fmac_f32_e32 v162, v101, v101
	v_fmac_f32_e32 v100, 0xbc000000, v48
	v_fmac_f32_e32 v162, v100, v100
	v_fmac_f32_e32 v99, 0xbc000000, v48
	v_fmac_f32_e32 v162, v99, v99
	v_fmac_f32_e32 v98, 0xbc000000, v48
	v_fmac_f32_e32 v162, v98, v98
	v_fmac_f32_e32 v97, 0xbc000000, v48
	global_load_dwordx4 v[12:15], v[32:33], off offset:48
	global_load_dwordx4 v[154:157], v[32:33], off offset:32
	global_load_dwordx4 v[16:19], v[30:31], off offset:48
	global_load_dwordx4 v[158:161], v[30:31], off offset:32
	v_fmac_f32_e32 v162, v97, v97
	v_fmac_f32_e32 v96, 0xbc000000, v48
	v_fmac_f32_e32 v162, v96, v96
	v_fmac_f32_e32 v95, 0xbc000000, v48
	v_fmac_f32_e32 v162, v95, v95
	v_fmac_f32_e32 v94, 0xbc000000, v48
	v_fmac_f32_e32 v162, v94, v94
	v_fmac_f32_e32 v93, 0xbc000000, v48
	v_fmac_f32_e32 v162, v93, v93
	v_fmac_f32_e32 v92, 0xbc000000, v48
	v_fmac_f32_e32 v162, v92, v92
	v_fmac_f32_e32 v91, 0xbc000000, v48
	v_fmac_f32_e32 v162, v91, v91
	v_fmac_f32_e32 v90, 0xbc000000, v48
	v_fmac_f32_e32 v162, v90, v90
	v_fmac_f32_e32 v89, 0xbc000000, v48
	v_fmac_f32_e32 v162, v89, v89
	v_fmac_f32_e32 v61, 0xbc000000, v48
	v_fmac_f32_e32 v162, v61, v61
	v_fmac_f32_e32 v60, 0xbc000000, v48
	v_fmac_f32_e32 v162, v60, v60
	v_fmac_f32_e32 v59, 0xbc000000, v48
	v_fmac_f32_e32 v162, v59, v59
	v_fmac_f32_e32 v57, 0xbc000000, v48
	v_fmac_f32_e32 v162, v57, v57
	v_fmac_f32_e32 v47, 0xbc000000, v48
	v_fmac_f32_e32 v162, v47, v47
	v_fmac_f32_e32 v46, 0xbc000000, v48
	v_fmac_f32_e32 v162, v46, v46
	v_fmac_f32_e32 v45, 0xbc000000, v48
	v_fmac_f32_e32 v162, v45, v45
	v_fmac_f32_e32 v44, 0xbc000000, v48
	v_fmac_f32_e32 v162, v44, v44
	v_fmac_f32_e32 v43, 0xbc000000, v48
	v_fmac_f32_e32 v162, v43, v43
	v_fmac_f32_e32 v42, 0xbc000000, v48
	v_fmac_f32_e32 v162, v42, v42
	v_fmac_f32_e32 v41, 0xbc000000, v48
	v_fmac_f32_e32 v162, v41, v41
	v_fmac_f32_e32 v40, 0xbc000000, v48
	v_fmac_f32_e32 v162, v40, v40
	v_fmac_f32_e32 v39, 0xbc000000, v48
	v_fmac_f32_e32 v162, v39, v39
	v_fmac_f32_e32 v38, 0xbc000000, v48
	v_fmac_f32_e32 v162, v38, v38
	v_fmac_f32_e32 v37, 0xbc000000, v48
	v_mul_f32_e32 v34, 0x3c000000, v48
	v_fmac_f32_e32 v162, v37, v37
	v_fmac_f32_e32 v36, 0xbc000000, v48
	v_fmac_f32_e32 v35, 0xbc000000, v48
	v_fmac_f32_e32 v162, v36, v36
	v_pk_add_f32 v[28:29], v[28:29], v[34:35] op_sel_hi:[1,0] neg_lo:[0,1] neg_hi:[0,1]
	v_fmac_f32_e32 v162, v35, v35
	v_pk_mul_f32 v[126:127], v[28:29], v[28:29]
	v_pk_add_f32 v[26:27], v[26:27], v[34:35] op_sel_hi:[1,0] neg_lo:[0,1] neg_hi:[0,1]
	v_add_f32_e32 v48, v127, v162
	v_add_f32_e32 v48, v126, v48
	v_pk_mul_f32 v[126:127], v[26:27], v[26:27]
	v_pk_add_f32 v[24:25], v[24:25], v[34:35] op_sel_hi:[1,0] neg_lo:[0,1] neg_hi:[0,1]
	v_add_f32_e32 v48, v127, v48
	v_add_f32_e32 v48, v126, v48
	v_pk_mul_f32 v[126:127], v[24:25], v[24:25]
	v_pk_add_f32 v[22:23], v[22:23], v[34:35] op_sel_hi:[1,0] neg_lo:[0,1] neg_hi:[0,1]
	v_add_f32_e32 v48, v127, v48
	v_add_f32_e32 v48, v126, v48
	v_pk_mul_f32 v[126:127], v[22:23], v[22:23]
	v_pk_add_f32 v[20:21], v[20:21], v[34:35] op_sel_hi:[1,0] neg_lo:[0,1] neg_hi:[0,1]
	v_add_f32_e32 v48, v127, v48
	v_add_f32_e32 v48, v126, v48
	v_pk_mul_f32 v[126:127], v[20:21], v[20:21]
	ds_write_b128 v132, v[0:3]
	v_add_f32_e32 v34, v127, v48
	v_add_f32_e32 v34, v126, v34
	ds_bpermute_b32 v48, v137, v34
	s_waitcnt vmcnt(8)
	v_cvt_pk_bf16_f32 v0, v8, v9
	v_cvt_pk_bf16_f32 v1, v10, v11
	v_cvt_pk_bf16_f32 v2, v4, v5
	global_load_dwordx4 v[8:11], v[32:33], off offset:80
	global_load_dwordx4 v[178:181], v[32:33], off offset:64
	global_load_dwordx4 v[182:185], v[30:31], off offset:80
	global_load_dwordx4 v[186:189], v[30:31], off offset:64
	s_waitcnt lgkmcnt(0)
	v_add_f32_e32 v3, v34, v48
	v_fmamk_f32 v3, v3, 0x3c000000, v88
	v_mul_f32_e32 v4, 0x4b800000, v3
	v_cmp_gt_f32_e64 s[0:1], s24, v3
	v_add_u32_e32 v5, v62, v71
	s_nop 0
	v_cndmask_b32_e64 v3, v3, v4, s[0:1]
	v_rsq_f32_e32 v4, v3
	v_cvt_pk_bf16_f32 v3, v6, v7
	ds_write_b128 v5, v[0:3]
	v_mul_f32_e32 v0, 0x45800000, v4
	v_cndmask_b32_e64 v34, v4, v0, s[0:1]
	v_mul_f32_e32 v0, v125, v34
	s_waitcnt vmcnt(8)
; __device__ __forceinline__ u16 f2bf(float f) { return (u16)(pack2(f, f) & 0xffffu); }
; __device__ void gmlp_item(const Params& p, int nb, int g, u16* smem) {
;     ...
;     const float rstd = rsqrtf(sq * (1.f / 128.f) + 1e-5f);
;     const int kt = s >> 6, kk = s & 63;
;     const float* lg = p.gm_ln_g + g * 128 + half * 64;
;     const float* lb = p.gm_ln_b + g * 128 + half * 64;
; #pragma unroll
;     for (int i = 0; i < 64; i++) {
;       int cc = half * 64 + i;
;       float val = (v[i] - mean) * rstd * lg[i] + lb[i];
;       sB[kt * 8192 + cc * 64 + (((kk >> 3) ^ ((cc >> 1) & 7)) << 3) + (kk & 7)] = f2bf(val);
;     }
	v_fma_f32 v0, v142, v0, v150
	v_cvt_pk_bf16_f32 v0, v0, s0
	ds_write_b16 v72, v0 offset:32768
	v_mul_f32_e32 v0, v124, v34
	v_fma_f32 v0, v143, v0, v151
	v_cvt_pk_bf16_f32 v0, v0, s0
	ds_write_b16 v72, v0 offset:32896
	v_mul_f32_e32 v0, v123, v34
	v_fma_f32 v0, v144, v0, v152
	v_cvt_pk_bf16_f32 v0, v0, s0
	ds_write_b16 v73, v0 offset:33024
	v_mul_f32_e32 v0, v122, v34
	v_fmac_f32_e32 v153, v145, v0
	v_cvt_pk_bf16_f32 v0, v153, s0
	ds_write_b16 v73, v0 offset:33152
	v_mul_f32_e32 v0, v121, v34
	v_fma_f32 v0, v138, v0, v146
	v_cvt_pk_bf16_f32 v0, v0, s0
	ds_write_b16 v74, v0 offset:33280
	v_mul_f32_e32 v0, v120, v34
	v_fma_f32 v0, v139, v0, v147
	v_cvt_pk_bf16_f32 v0, v0, s0
	ds_write_b16 v74, v0 offset:33408
	v_mul_f32_e32 v0, v119, v34
	v_fma_f32 v48, v140, v0, v148
	global_load_dwordx4 v[0:3], v[32:33], off offset:112
	global_load_dwordx4 v[120:123], v[32:33], off offset:96
	global_load_dwordx4 v[4:7], v[30:31], off offset:112
	global_load_dwordx4 v[124:127], v[30:31], off offset:96
	v_cvt_pk_bf16_f32 v48, v48, s0
	ds_write_b16 v75, v48 offset:33536
	v_mul_f32_e32 v48, v118, v34
	v_fmac_f32_e32 v149, v141, v48
	v_cvt_pk_bf16_f32 v48, v149, s0
	ds_write_b16 v75, v48 offset:33664
	v_mul_f32_e32 v48, v117, v34
	s_waitcnt vmcnt(8)
	v_fma_f32 v48, v154, v48, v158
	v_cvt_pk_bf16_f32 v48, v48, s0
	ds_write_b16 v76, v48 offset:33792
	v_mul_f32_e32 v48, v116, v34
	v_fma_f32 v48, v155, v48, v159
	v_cvt_pk_bf16_f32 v48, v48, s0
	ds_write_b16 v76, v48 offset:33920
	v_mul_f32_e32 v48, v115, v34
	v_fma_f32 v48, v156, v48, v160
	v_cvt_pk_bf16_f32 v48, v48, s0
	ds_write_b16 v77, v48 offset:34048
	v_mul_f32_e32 v48, v114, v34
	v_fmac_f32_e32 v161, v157, v48
	v_cvt_pk_bf16_f32 v48, v161, s0
	ds_write_b16 v77, v48 offset:34176
	v_mul_f32_e32 v48, v113, v34
	v_fma_f32 v12, v12, v48, v16
	v_cvt_pk_bf16_f32 v12, v12, s0
	ds_write_b16 v78, v12 offset:34304
	v_mul_f32_e32 v12, v112, v34
	v_fma_f32 v12, v13, v12, v17
	v_cvt_pk_bf16_f32 v12, v12, s0
	ds_write_b16 v78, v12 offset:34432
	global_load_dwordx4 v[112:115], v[32:33], off offset:144
	global_load_dwordx4 v[116:119], v[32:33], off offset:128
	global_load_dwordx4 v[138:141], v[30:31], off offset:144
	global_load_dwordx4 v[142:145], v[30:31], off offset:128
	v_mul_f32_e32 v12, v111, v34
	v_fma_f32 v12, v14, v12, v18
	v_cvt_pk_bf16_f32 v12, v12, s0
	ds_write_b16 v79, v12 offset:34560
	v_mul_f32_e32 v12, v110, v34
	v_fmac_f32_e32 v19, v15, v12
	v_cvt_pk_bf16_f32 v12, v19, s0
	ds_write_b16 v79, v12 offset:34688
	v_mul_f32_e32 v12, v109, v34
	s_waitcnt vmcnt(8)
	v_fma_f32 v12, v178, v12, v186
	v_cvt_pk_bf16_f32 v12, v12, s0
	ds_write_b16 v72, v12 offset:34816
	v_mul_f32_e32 v12, v108, v34
	v_fma_f32 v12, v179, v12, v187
	v_cvt_pk_bf16_f32 v12, v12, s0
	ds_write_b16 v72, v12 offset:34944
	v_mul_f32_e32 v12, v107, v34
	v_fma_f32 v12, v180, v12, v188
	v_cvt_pk_bf16_f32 v12, v12, s0
	ds_write_b16 v73, v12 offset:35072
	v_mul_f32_e32 v12, v106, v34
	v_fmac_f32_e32 v189, v181, v12
	v_cvt_pk_bf16_f32 v12, v189, s0
	ds_write_b16 v73, v12 offset:35200
	v_mul_f32_e32 v12, v105, v34
	v_fma_f32 v8, v8, v12, v182
	v_cvt_pk_bf16_f32 v8, v8, s0
	ds_write_b16 v74, v8 offset:35328
	v_mul_f32_e32 v8, v104, v34
	v_fma_f32 v8, v9, v8, v183
	v_cvt_pk_bf16_f32 v8, v8, s0
	ds_write_b16 v74, v8 offset:35456
	global_load_dwordx4 v[12:15], v[32:33], off offset:176
	global_load_dwordx4 v[16:19], v[32:33], off offset:160
	global_load_dwordx4 v[104:107], v[30:31], off offset:176
	global_load_dwordx4 v[108:111], v[30:31], off offset:160
	v_mul_f32_e32 v8, v103, v34
	v_fma_f32 v8, v10, v8, v184
	v_cvt_pk_bf16_f32 v8, v8, s0
	ds_write_b16 v75, v8 offset:35584
	v_mul_f32_e32 v8, v102, v34
	v_fmac_f32_e32 v185, v11, v8
	v_cvt_pk_bf16_f32 v8, v185, s0
	ds_write_b16 v75, v8 offset:35712
	v_mul_f32_e32 v8, v101, v34
	s_waitcnt vmcnt(8)
	v_fma_f32 v8, v120, v8, v124
	v_cvt_pk_bf16_f32 v8, v8, s0
	ds_write_b16 v76, v8 offset:35840
	v_mul_f32_e32 v8, v100, v34
	v_fma_f32 v8, v121, v8, v125
	v_cvt_pk_bf16_f32 v8, v8, s0
	ds_write_b16 v76, v8 offset:35968
	v_mul_f32_e32 v8, v99, v34
	v_fma_f32 v8, v122, v8, v126
	v_cvt_pk_bf16_f32 v8, v8, s0
	ds_write_b16 v77, v8 offset:36096
	v_mul_f32_e32 v8, v98, v34
	v_fmac_f32_e32 v127, v123, v8
	v_cvt_pk_bf16_f32 v8, v127, s0
	ds_write_b16 v77, v8 offset:36224
	v_mul_f32_e32 v8, v97, v34
	v_fma_f32 v0, v0, v8, v4
	v_cvt_pk_bf16_f32 v0, v0, s0
	ds_write_b16 v78, v0 offset:36352
	v_mul_f32_e32 v0, v96, v34
	global_load_dwordx4 v[8:11], v[32:33], off offset:208
	global_load_dwordx4 v[96:99], v[32:33], off offset:192
	global_load_dwordx4 v[100:103], v[30:31], off offset:208
	global_load_dwordx4 v[120:123], v[30:31], off offset:192
	v_fma_f32 v0, v1, v0, v5
	v_cvt_pk_bf16_f32 v0, v0, s0
	ds_write_b16 v78, v0 offset:36480
	v_mul_f32_e32 v0, v95, v34
	v_fma_f32 v0, v2, v0, v6
	v_cvt_pk_bf16_f32 v0, v0, s0
	ds_write_b16 v79, v0 offset:36608
	v_mul_f32_e32 v0, v94, v34
	v_fmac_f32_e32 v7, v3, v0
	v_cvt_pk_bf16_f32 v0, v7, s0
	ds_write_b16 v79, v0 offset:36736
	v_mul_f32_e32 v0, v93, v34
	s_waitcnt vmcnt(8)
; __device__ __forceinline__ u16 f2bf(float f) { return (u16)(pack2(f, f) & 0xffffu); }
; __device__ void gmlp_item(const Params& p, int nb, int g, u16* smem) {
;     ...
; #pragma unroll
;     for (int i = 0; i < 64; i++) {
;       int cc = half * 64 + i;
;       float val = (v[i] - mean) * rstd * lg[i] + lb[i];
;       sB[kt * 8192 + cc * 64 + (((kk >> 3) ^ ((cc >> 1) & 7)) << 3) + (kk & 7)] = f2bf(val);
;     }
;   }
;   __syncthreads();
	v_fma_f32 v0, v116, v0, v142
	v_cvt_pk_bf16_f32 v0, v0, s0
	ds_write_b16 v72, v0 offset:36864
	v_mul_f32_e32 v0, v92, v34
	v_fma_f32 v0, v117, v0, v143
	v_cvt_pk_bf16_f32 v0, v0, s0
	ds_write_b16 v72, v0 offset:36992
	v_mul_f32_e32 v0, v91, v34
	v_fma_f32 v0, v118, v0, v144
	v_cvt_pk_bf16_f32 v0, v0, s0
	ds_write_b16 v73, v0 offset:37120
	v_mul_f32_e32 v0, v90, v34
	v_fmac_f32_e32 v145, v119, v0
	v_cvt_pk_bf16_f32 v0, v145, s0
	ds_write_b16 v73, v0 offset:37248
	v_mul_f32_e32 v0, v89, v34
	v_fma_f32 v48, v112, v0, v138
	global_load_dwordx4 v[0:3], v[32:33], off offset:240
	global_load_dwordx4 v[4:7], v[32:33], off offset:224
	global_load_dwordx4 v[90:93], v[30:31], off offset:240
	s_nop 0
	global_load_dwordx4 v[30:33], v[30:31], off offset:224
	v_cvt_pk_bf16_f32 v48, v48, s0
	ds_write_b16 v74, v48 offset:37376
	v_mul_f32_e32 v48, v61, v34
	v_fma_f32 v48, v48, v113, v139
	v_cvt_pk_bf16_f32 v48, v48, s0
	ds_write_b16 v74, v48 offset:37504
	v_mul_f32_e32 v48, v60, v34
	v_fma_f32 v48, v48, v114, v140
	v_cvt_pk_bf16_f32 v48, v48, s0
	ds_write_b16 v75, v48 offset:37632
	v_mul_f32_e32 v48, v59, v34
	v_fmac_f32_e32 v141, v48, v115
	v_cvt_pk_bf16_f32 v48, v141, s0
	ds_write_b16 v75, v48 offset:37760
	v_mul_f32_e32 v48, v57, v34
	s_waitcnt vmcnt(8)
	v_fma_f32 v16, v48, v16, v108
	v_cvt_pk_bf16_f32 v16, v16, s0
	ds_write_b16 v76, v16 offset:37888
	v_mul_f32_e32 v16, v47, v34
	v_fma_f32 v16, v16, v17, v109
	v_cvt_pk_bf16_f32 v16, v16, s0
	ds_write_b16 v76, v16 offset:38016
	v_mul_f32_e32 v16, v46, v34
	v_fma_f32 v16, v16, v18, v110
	v_cvt_pk_bf16_f32 v16, v16, s0
	ds_write_b16 v77, v16 offset:38144
	v_mul_f32_e32 v16, v45, v34
	v_fmac_f32_e32 v111, v16, v19
	v_cvt_pk_bf16_f32 v16, v111, s0
	ds_write_b16 v77, v16 offset:38272
	v_mul_f32_e32 v16, v44, v34
	v_fma_f32 v12, v16, v12, v104
	v_cvt_pk_bf16_f32 v12, v12, s0
	ds_write_b16 v78, v12 offset:38400
	v_mul_f32_e32 v12, v43, v34
	v_fma_f32 v12, v12, v13, v105
	v_cvt_pk_bf16_f32 v12, v12, s0
	ds_write_b16 v78, v12 offset:38528
	v_mul_f32_e32 v12, v42, v34
	v_fma_f32 v12, v12, v14, v106
	v_cvt_pk_bf16_f32 v12, v12, s0
	ds_write_b16 v79, v12 offset:38656
	v_mul_f32_e32 v12, v41, v34
	v_fmac_f32_e32 v107, v12, v15
	v_cvt_pk_bf16_f32 v12, v107, s0
	ds_write_b16 v79, v12 offset:38784
	v_mul_f32_e32 v12, v40, v34
	s_waitcnt vmcnt(4)
	v_fma_f32 v12, v12, v96, v120
	v_cvt_pk_bf16_f32 v12, v12, s0
	ds_write_b16 v72, v12 offset:38912
	v_mul_f32_e32 v12, v39, v34
	v_fma_f32 v12, v12, v97, v121
	v_cvt_pk_bf16_f32 v12, v12, s0
	ds_write_b16 v72, v12 offset:39040
	v_mul_f32_e32 v12, v38, v34
	v_fma_f32 v12, v12, v98, v122
	v_cvt_pk_bf16_f32 v12, v12, s0
	ds_write_b16 v73, v12 offset:39168
	v_mul_f32_e32 v12, v37, v34
	v_fmac_f32_e32 v123, v12, v99
	v_cvt_pk_bf16_f32 v12, v123, s0
	ds_write_b16 v73, v12 offset:39296
	v_mul_f32_e32 v12, v36, v34
	v_fma_f32 v8, v12, v8, v100
	v_cvt_pk_bf16_f32 v8, v8, s0
	ds_write_b16 v74, v8 offset:39424
	v_mul_f32_e32 v8, v35, v34
	v_fma_f32 v8, v8, v9, v101
	v_cvt_pk_bf16_f32 v8, v8, s0
	ds_write_b16 v74, v8 offset:39552
	v_mul_f32_e32 v8, v29, v34
	v_fma_f32 v8, v8, v10, v102
	v_cvt_pk_bf16_f32 v8, v8, s0
	ds_write_b16 v75, v8 offset:39680
	v_mul_f32_e32 v8, v28, v34
	v_fmac_f32_e32 v103, v8, v11
	v_cvt_pk_bf16_f32 v8, v103, s0
	ds_write_b16 v75, v8 offset:39808
	v_mul_f32_e32 v8, v27, v34
	s_waitcnt vmcnt(0)
	v_fma_f32 v4, v8, v4, v30
	v_cvt_pk_bf16_f32 v4, v4, s0
	ds_write_b16 v76, v4 offset:39936
	v_mul_f32_e32 v4, v26, v34
	v_fma_f32 v4, v4, v5, v31
	v_cvt_pk_bf16_f32 v4, v4, s0
	ds_write_b16 v76, v4 offset:40064
	v_mul_f32_e32 v4, v25, v34
	v_fma_f32 v4, v4, v6, v32
	v_cvt_pk_bf16_f32 v4, v4, s0
	ds_write_b16 v77, v4 offset:40192
	v_mul_f32_e32 v4, v24, v34
	v_fmac_f32_e32 v33, v4, v7
	v_cvt_pk_bf16_f32 v4, v33, s0
	ds_write_b16 v77, v4 offset:40320
	v_mul_f32_e32 v4, v23, v34
	v_fma_f32 v0, v4, v0, v90
	v_cvt_pk_bf16_f32 v0, v0, s0
	ds_write_b16 v78, v0 offset:40448
	v_mul_f32_e32 v0, v22, v34
	v_fma_f32 v0, v0, v1, v91
	v_cvt_pk_bf16_f32 v0, v0, s0
	ds_write_b16 v78, v0 offset:40576
	v_mul_f32_e32 v0, v21, v34
	v_fma_f32 v0, v0, v2, v92
	v_cvt_pk_bf16_f32 v0, v0, s0
	ds_write_b16 v79, v0 offset:40704
	v_mul_f32_e32 v0, v20, v34
	v_fmac_f32_e32 v93, v0, v3
	v_cvt_pk_bf16_f32 v0, v93, s0
	ds_write_b16 v79, v0 offset:40832
	s_waitcnt lgkmcnt(0)
	s_barrier
; __device__ __forceinline__ void mma_128x128x64(const u16* sA, const u16* sB, f32x4 (&acc)[4][4], int wr, int wc, int fr, int fq) {
;   bf16x8 af[2][4], bfr[2][4];
; #pragma unroll
;   for (int ks = 0; ks < 2; ks++) {
; #pragma unroll
;     for (int mt = 0; mt < 4; mt++) {
;       int row = wr * 64 + mt * 16 + fr;
;       int ch = (ks * 4 + fq) ^ ((row >> 1) & 7);
;       af[ks][mt] = *(const bf16x8*)(sA + row * 64 + ch * 8);
;     }
; #pragma unroll
;     for (int nt = 0; nt < 4; nt++) {
;       int row = wc * 64 + nt * 16 + fr;
;       int ch = (ks * 4 + fq) ^ ((row >> 1) & 7);
;       bfr[ks][nt] = *(const bf16x8*)(sB + row * 64 + ch * 8);
;     }
;   }
;   __builtin_amdgcn_sched_barrier(0);
;   __builtin_amdgcn_s_setprio(1);
; #pragma unroll
;   for (int ks = 0; ks < 2; ks++)
; #pragma unroll
;     for (int mt = 0; mt < 4; mt++)
; #pragma unroll
;       for (int nt = 0; nt < 4; nt++)
;         acc[mt][nt] = __builtin_amdgcn_mfma_f32_16x16x32_bf16(bfr[ks][nt], af[ks][mt], acc[mt][nt], 0, 0, 0);
;   __builtin_amdgcn_s_setprio(0);
; }
; __device__ void gmlp_item(const Params& p, int nb, int g, u16* smem) {
;     ...
;   mma_128x128x64(sA, sB, acc, wr, wc, fr, fq);
;   mma_128x128x64(sA + 8192, sB + 8192, acc, wr, wc, fr, fq);
	ds_read_b128 v[0:3], v80
	ds_read_b128 v[4:7], v80 offset:2048
	ds_read_b128 v[8:11], v80 offset:4096
	ds_read_b128 v[12:15], v80 offset:6144
	ds_read_b128 v[16:19], v81 offset:32768
	ds_read_b128 v[20:23], v81 offset:34816
	ds_read_b128 v[24:27], v81 offset:36864
	ds_read_b128 v[28:31], v81 offset:38912
	ds_read_b128 v[32:35], v82
	ds_read_b128 v[36:39], v82 offset:2048
	ds_read_b128 v[40:43], v82 offset:4096
	ds_read_b128 v[44:47], v82 offset:6144
	ds_read_b128 v[90:93], v83 offset:32768
	ds_read_b128 v[94:97], v83 offset:34816
	ds_read_b128 v[98:101], v83 offset:36864
	ds_read_b128 v[102:105], v83 offset:38912
	s_lshl_b32 s0, s27, 7
	s_setprio 1
	s_waitcnt lgkmcnt(11)
	v_mfma_f32_16x16x32_bf16 v[106:109], v[16:19], v[0:3], 0
	s_waitcnt lgkmcnt(10)
	v_mfma_f32_16x16x32_bf16 v[110:113], v[20:23], v[0:3], 0
	s_waitcnt lgkmcnt(9)
	v_mfma_f32_16x16x32_bf16 v[114:117], v[24:27], v[0:3], 0
	s_waitcnt lgkmcnt(8)
	v_mfma_f32_16x16x32_bf16 v[0:3], v[28:31], v[0:3], 0
	v_mfma_f32_16x16x32_bf16 v[118:121], v[16:19], v[4:7], 0
	v_mfma_f32_16x16x32_bf16 v[122:125], v[20:23], v[4:7], 0
	v_mfma_f32_16x16x32_bf16 v[138:141], v[24:27], v[4:7], 0
	v_mfma_f32_16x16x32_bf16 v[4:7], v[28:31], v[4:7], 0
	v_mfma_f32_16x16x32_bf16 v[142:145], v[16:19], v[8:11], 0
	v_mfma_f32_16x16x32_bf16 v[146:149], v[20:23], v[8:11], 0
	v_mfma_f32_16x16x32_bf16 v[150:153], v[24:27], v[8:11], 0
	v_mfma_f32_16x16x32_bf16 v[8:11], v[28:31], v[8:11], 0
	v_mfma_f32_16x16x32_bf16 v[16:19], v[16:19], v[12:15], 0
	v_mfma_f32_16x16x32_bf16 v[20:23], v[20:23], v[12:15], 0
	v_mfma_f32_16x16x32_bf16 v[24:27], v[24:27], v[12:15], 0
	v_mfma_f32_16x16x32_bf16 v[12:15], v[28:31], v[12:15], 0
	s_waitcnt lgkmcnt(3)
	v_mfma_f32_16x16x32_bf16 v[28:31], v[90:93], v[32:35], v[106:109]
	s_waitcnt lgkmcnt(2)
	v_mfma_f32_16x16x32_bf16 v[106:109], v[94:97], v[32:35], v[110:113]
	s_waitcnt lgkmcnt(1)
	v_mfma_f32_16x16x32_bf16 v[110:113], v[98:101], v[32:35], v[114:117]
	s_waitcnt lgkmcnt(0)
	v_mfma_f32_16x16x32_bf16 v[0:3], v[102:105], v[32:35], v[0:3]
	v_mfma_f32_16x16x32_bf16 v[32:35], v[90:93], v[36:39], v[118:121]
	v_mfma_f32_16x16x32_bf16 v[114:117], v[94:97], v[36:39], v[122:125]
	v_mfma_f32_16x16x32_bf16 v[118:121], v[98:101], v[36:39], v[138:141]
	v_mfma_f32_16x16x32_bf16 v[4:7], v[102:105], v[36:39], v[4:7]
	v_mfma_f32_16x16x32_bf16 v[36:39], v[90:93], v[40:43], v[142:145]
	v_mfma_f32_16x16x32_bf16 v[122:125], v[94:97], v[40:43], v[146:149]
	v_mfma_f32_16x16x32_bf16 v[138:141], v[98:101], v[40:43], v[150:153]
	v_mfma_f32_16x16x32_bf16 v[8:11], v[102:105], v[40:43], v[8:11]
	v_mfma_f32_16x16x32_bf16 v[16:19], v[90:93], v[44:47], v[16:19]
	v_mfma_f32_16x16x32_bf16 v[20:23], v[94:97], v[44:47], v[20:23]
	v_mfma_f32_16x16x32_bf16 v[24:27], v[98:101], v[44:47], v[24:27]
	v_mfma_f32_16x16x32_bf16 v[12:15], v[102:105], v[44:47], v[12:15]
	s_setprio 0
	ds_read_b128 v[40:43], v80 offset:16384
	ds_read_b128 v[44:47], v80 offset:18432
	ds_read_b128 v[90:93], v80 offset:20480
	ds_read_b128 v[94:97], v80 offset:22528
	ds_read_b128 v[98:101], v81 offset:49152
	ds_read_b128 v[102:105], v81 offset:51200
	ds_read_b128 v[142:145], v81 offset:53248
	ds_read_b128 v[146:149], v81 offset:55296
	ds_read_b128 v[150:153], v82 offset:16384
	ds_read_b128 v[154:157], v82 offset:18432
	ds_read_b128 v[158:161], v82 offset:20480
	ds_read_b128 v[178:181], v82 offset:22528
	ds_read_b128 v[182:185], v83 offset:49152
	ds_read_b128 v[186:189], v83 offset:51200
	ds_read_b128 v[190:193], v83 offset:53248
	ds_read_b128 v[194:197], v83 offset:55296
	s_setprio 1
	s_waitcnt lgkmcnt(11)
	v_mfma_f32_16x16x32_bf16 v[28:31], v[98:101], v[40:43], v[28:31]
	s_waitcnt lgkmcnt(10)
	v_mfma_f32_16x16x32_bf16 v[106:109], v[102:105], v[40:43], v[106:109]
	s_waitcnt lgkmcnt(9)
	v_mfma_f32_16x16x32_bf16 v[110:113], v[142:145], v[40:43], v[110:113]
	s_waitcnt lgkmcnt(8)
	v_mfma_f32_16x16x32_bf16 v[0:3], v[146:149], v[40:43], v[0:3]
	v_mfma_f32_16x16x32_bf16 v[32:35], v[98:101], v[44:47], v[32:35]
	v_mfma_f32_16x16x32_bf16 v[40:43], v[102:105], v[44:47], v[114:117]
	v_mfma_f32_16x16x32_bf16 v[114:117], v[142:145], v[44:47], v[118:121]
	v_mfma_f32_16x16x32_bf16 v[4:7], v[146:149], v[44:47], v[4:7]
	v_mfma_f32_16x16x32_bf16 v[118:121], v[98:101], v[90:93], v[36:39]
	v_mfma_f32_16x16x32_bf16 v[122:125], v[102:105], v[90:93], v[122:125]
	v_mfma_f32_16x16x32_bf16 v[138:141], v[142:145], v[90:93], v[138:141]
	v_mfma_f32_16x16x32_bf16 v[8:11], v[146:149], v[90:93], v[8:11]
	v_mfma_f32_16x16x32_bf16 v[90:93], v[98:101], v[94:97], v[16:19]
	v_mfma_f32_16x16x32_bf16 v[98:101], v[102:105], v[94:97], v[20:23]
	v_mfma_f32_16x16x32_bf16 v[102:105], v[142:145], v[94:97], v[24:27]
	v_mfma_f32_16x16x32_bf16 v[94:97], v[146:149], v[94:97], v[12:15]
	s_waitcnt lgkmcnt(3)
	v_mfma_f32_16x16x32_bf16 v[142:145], v[182:185], v[150:153], v[28:31]
	s_waitcnt lgkmcnt(2)
	v_mfma_f32_16x16x32_bf16 v[106:109], v[186:189], v[150:153], v[106:109]
	s_waitcnt lgkmcnt(1)
	v_mfma_f32_16x16x32_bf16 v[110:113], v[190:193], v[150:153], v[110:113]
	s_waitcnt lgkmcnt(0)
; __device__ __forceinline__ float bflo(uint32_t w) { return __uint_as_float(w << 16); }
; __device__ __forceinline__ float bfhi(uint32_t w) { return __uint_as_float(w & 0xffff0000u); }
; __device__ void gmlp_item(const Params& p, int nb, int g, u16* smem) {
;     ...
; #pragma unroll
;   for (int mt = 0; mt < 4; mt++) {
;     int m = wr * 64 + mt * 16 + fr;
;     float bs = p.gm_b_s[g * 128 + m];
;     const u16* up = p.proj() + (long)(nb * 128 + m) * INW + g * 128;
;     u16* op = p.mixcat() + (long)(nb * 128 + m) * DM + g * 128;
; #pragma unroll
;     for (int nt = 0; nt < 4; nt++) {
;       int n = wc * 64 + nt * 16 + fq * 4;
;       uint2 uw = *(const uint2*)(up + n);
;       f32x4 a = acc[mt][nt];
;       store_bf4(op + n, bflo(uw.x) * (a[0] + bs), bfhi(uw.x) * (a[1] + bs), bflo(uw.y) * (a[2] + bs), bfhi(uw.y) * (a[3] + bs));
;     }
;   }
; __device__ void phase_mix(const Params& p, u16* smem) {
;     ...
;   for (int j = blockIdx.x; j < NG; j += gridDim.x) gmlp_item(p, j >> 3, j & 7, smem);
	v_mfma_f32_16x16x32_bf16 v[146:149], v[194:197], v[150:153], v[0:3]
	v_mfma_f32_16x16x32_bf16 v[44:47], v[182:185], v[154:157], v[32:35]
	v_mfma_f32_16x16x32_bf16 v[40:43], v[186:189], v[154:157], v[40:43]
	v_mfma_f32_16x16x32_bf16 v[36:39], v[190:193], v[154:157], v[114:117]
	v_mfma_f32_16x16x32_bf16 v[32:35], v[194:197], v[154:157], v[4:7]
	v_mfma_f32_16x16x32_bf16 v[28:31], v[182:185], v[158:161], v[118:121]
	v_mfma_f32_16x16x32_bf16 v[24:27], v[186:189], v[158:161], v[122:125]
	v_mfma_f32_16x16x32_bf16 v[20:23], v[190:193], v[158:161], v[138:141]
	v_mfma_f32_16x16x32_bf16 v[16:19], v[194:197], v[158:161], v[8:11]
	v_mfma_f32_16x16x32_bf16 v[12:15], v[182:185], v[178:181], v[90:93]
	v_mfma_f32_16x16x32_bf16 v[8:11], v[186:189], v[178:181], v[98:101]
	v_mfma_f32_16x16x32_bf16 v[4:7], v[190:193], v[178:181], v[102:105]
	v_mfma_f32_16x16x32_bf16 v[0:3], v[194:197], v[178:181], v[94:97]
	s_setprio 0
	v_add_u32_e32 v90, s26, v84
	v_mov_b64_e32 v[60:61], s[34:35]
	v_add_lshl_u32 v57, s0, v84, 2
	v_mad_i64_i32 v[92:93], s[0:1], v90, s2, v[60:61]
	v_mov_b32_e32 v59, v49
	v_lshl_add_u64 v[92:93], v[92:93], 0, s[18:19]
	global_load_dword v48, v57, s[88:89]
	v_lshl_add_u64 v[92:93], v[92:93], 0, v[58:59]
	global_load_dwordx2 v[94:95], v[92:93], off
	global_load_dwordx2 v[96:97], v[92:93], off offset:32
	global_load_dwordx2 v[98:99], v[92:93], off offset:64
	s_nop 0
	global_load_dwordx2 v[92:93], v[92:93], off offset:96
	v_ashrrev_i32_e32 v91, 31, v90
	v_lshlrev_b64 v[90:91], 12, v[90:91]
	v_add_u32_e32 v100, s26, v85
	v_lshl_add_u64 v[90:91], s[16:17], 0, v[90:91]
	v_mad_i64_i32 v[102:103], s[0:1], v100, s2, v[60:61]
	v_lshl_add_u64 v[90:91], v[90:91], 0, s[18:19]
	v_lshl_add_u64 v[102:103], v[102:103], 0, s[18:19]
	v_lshl_add_u64 v[90:91], v[90:91], 0, v[58:59]
	v_lshl_add_u64 v[102:103], v[102:103], 0, v[58:59]
	v_ashrrev_i32_e32 v101, 31, v100
	v_lshlrev_b64 v[100:101], 12, v[100:101]
	v_lshl_add_u64 v[100:101], s[16:17], 0, v[100:101]
	v_lshl_add_u64 v[100:101], v[100:101], 0, s[18:19]
	v_lshl_add_u64 v[100:101], v[100:101], 0, v[58:59]
	s_lshr_b32 m0, s94, 1
	s_add_i32 s25, s25, m0
	s_lshr_b32 m0, s22, 1
	s_add_i32 s3, s3, m0
	s_cmpk_lt_i32 s25, 0x200
	s_waitcnt vmcnt(3)
	v_lshlrev_b32_e32 v120, 16, v94
	v_pk_add_f32 v[104:105], v[142:143], v[48:49] op_sel_hi:[1,0]
	v_pk_add_f32 v[114:115], v[144:145], v[48:49] op_sel_hi:[1,0]
	v_and_b32_e32 v121, 0xffff0000, v94
	v_lshlrev_b32_e32 v94, 16, v95
	v_and_b32_e32 v95, 0xffff0000, v95
	v_pk_add_f32 v[106:107], v[106:107], v[48:49] op_sel_hi:[1,0]
	v_pk_add_f32 v[108:109], v[108:109], v[48:49] op_sel_hi:[1,0]
	v_pk_add_f32 v[110:111], v[110:111], v[48:49] op_sel_hi:[1,0]
	v_pk_add_f32 v[112:113], v[112:113], v[48:49] op_sel_hi:[1,0]
	v_pk_add_f32 v[116:117], v[146:147], v[48:49] op_sel_hi:[1,0]
	v_pk_add_f32 v[118:119], v[148:149], v[48:49] op_sel_hi:[1,0]
	s_waitcnt vmcnt(2)
	v_lshlrev_b32_e32 v122, 16, v96
	v_and_b32_e32 v123, 0xffff0000, v96
	v_lshlrev_b32_e32 v96, 16, v97
	v_and_b32_e32 v97, 0xffff0000, v97
	s_waitcnt vmcnt(1)
	v_lshlrev_b32_e32 v124, 16, v98
	v_and_b32_e32 v125, 0xffff0000, v98
	v_lshlrev_b32_e32 v98, 16, v99
	v_and_b32_e32 v99, 0xffff0000, v99
	s_waitcnt vmcnt(0)
	v_lshlrev_b32_e32 v126, 16, v92
	v_and_b32_e32 v127, 0xffff0000, v92
	v_lshlrev_b32_e32 v92, 16, v93
	v_and_b32_e32 v93, 0xffff0000, v93
	v_pk_mul_f32 v[104:105], v[104:105], v[120:121]
	v_pk_mul_f32 v[94:95], v[114:115], v[94:95]
	v_pk_mul_f32 v[106:107], v[106:107], v[122:123]
	v_pk_mul_f32 v[96:97], v[108:109], v[96:97]
	v_pk_mul_f32 v[108:109], v[110:111], v[124:125]
	v_pk_mul_f32 v[98:99], v[112:113], v[98:99]
	v_pk_mul_f32 v[110:111], v[116:117], v[126:127]
	v_pk_mul_f32 v[92:93], v[118:119], v[92:93]
	v_cvt_pk_bf16_f32 v104, v104, v105
	v_cvt_pk_bf16_f32 v105, v94, v95
	v_cvt_pk_bf16_f32 v94, v106, v107
	v_cvt_pk_bf16_f32 v95, v96, v97
	v_cvt_pk_bf16_f32 v96, v108, v109
	v_cvt_pk_bf16_f32 v97, v98, v99
	v_cvt_pk_bf16_f32 v98, v110, v111
	v_cvt_pk_bf16_f32 v99, v92, v93
	global_store_dwordx2 v[90:91], v[104:105], off
	global_store_dwordx2 v[90:91], v[94:95], off offset:32
	global_store_dwordx2 v[90:91], v[96:97], off offset:64
	global_load_dwordx2 v[92:93], v[102:103], off
	s_waitcnt vmcnt(0)
	v_lshlrev_b32_e32 v104, 16, v92
	global_store_dwordx2 v[90:91], v[98:99], off offset:96
	global_load_dword v48, v57, s[88:89] offset:64
	s_nop 0
	global_load_dwordx2 v[90:91], v[102:103], off offset:32
	global_load_dwordx2 v[94:95], v[102:103], off offset:64
	global_load_dwordx2 v[96:97], v[102:103], off offset:96
	v_add_u32_e32 v98, s26, v86
	v_and_b32_e32 v105, 0xffff0000, v92
	v_lshlrev_b32_e32 v92, 16, v93
	v_and_b32_e32 v93, 0xffff0000, v93
	v_mad_i64_i32 v[102:103], s[0:1], v98, s2, v[60:61]
	v_lshl_add_u64 v[102:103], v[102:103], 0, s[18:19]
	v_lshl_add_u64 v[102:103], v[102:103], 0, v[58:59]
	v_ashrrev_i32_e32 v99, 31, v98
	s_waitcnt vmcnt(3)
	v_pk_add_f32 v[44:45], v[44:45], v[48:49] op_sel_hi:[1,0]
	v_pk_add_f32 v[46:47], v[46:47], v[48:49] op_sel_hi:[1,0]
	s_waitcnt vmcnt(2)
	v_lshlrev_b32_e32 v106, 16, v90
	v_and_b32_e32 v107, 0xffff0000, v90
	v_pk_add_f32 v[40:41], v[40:41], v[48:49] op_sel_hi:[1,0]
	v_lshlrev_b32_e32 v90, 16, v91
	v_and_b32_e32 v91, 0xffff0000, v91
	v_pk_add_f32 v[42:43], v[42:43], v[48:49] op_sel_hi:[1,0]
	s_waitcnt vmcnt(1)
	v_lshlrev_b32_e32 v108, 16, v94
	v_and_b32_e32 v109, 0xffff0000, v94
	v_pk_add_f32 v[36:37], v[36:37], v[48:49] op_sel_hi:[1,0]
	v_lshlrev_b32_e32 v94, 16, v95
	v_and_b32_e32 v95, 0xffff0000, v95
	v_pk_add_f32 v[38:39], v[38:39], v[48:49] op_sel_hi:[1,0]
	s_waitcnt vmcnt(0)
; __device__ __forceinline__ float bflo(uint32_t w) { return __uint_as_float(w << 16); }
; __device__ __forceinline__ float bfhi(uint32_t w) { return __uint_as_float(w & 0xffff0000u); }
; __device__ void gmlp_item(const Params& p, int nb, int g, u16* smem) {
;     ...
; #pragma unroll
;   for (int mt = 0; mt < 4; mt++) {
;     int m = wr * 64 + mt * 16 + fr;
;     float bs = p.gm_b_s[g * 128 + m];
;     const u16* up = p.proj() + (long)(nb * 128 + m) * INW + g * 128;
;     u16* op = p.mixcat() + (long)(nb * 128 + m) * DM + g * 128;
; #pragma unroll
;     for (int nt = 0; nt < 4; nt++) {
;       int n = wc * 64 + nt * 16 + fq * 4;
;       uint2 uw = *(const uint2*)(up + n);
;       f32x4 a = acc[mt][nt];
;       store_bf4(op + n, bflo(uw.x) * (a[0] + bs), bfhi(uw.x) * (a[1] + bs), bflo(uw.y) * (a[2] + bs), bfhi(uw.y) * (a[3] + bs));
;     }
;   }
;   __syncthreads();
; __device__ void phase_mix(const Params& p, u16* smem) {
;     ...
;   for (int j = blockIdx.x; j < NG; j += gridDim.x) gmlp_item(p, j >> 3, j & 7, smem);
	v_lshlrev_b32_e32 v110, 16, v96
	v_and_b32_e32 v111, 0xffff0000, v96
	v_pk_add_f32 v[32:33], v[32:33], v[48:49] op_sel_hi:[1,0]
	v_lshlrev_b32_e32 v96, 16, v97
	v_and_b32_e32 v97, 0xffff0000, v97
	v_pk_add_f32 v[34:35], v[34:35], v[48:49] op_sel_hi:[1,0]
	v_pk_mul_f32 v[44:45], v[44:45], v[104:105]
	v_pk_mul_f32 v[46:47], v[46:47], v[92:93]
	v_pk_mul_f32 v[40:41], v[40:41], v[106:107]
	v_pk_mul_f32 v[42:43], v[42:43], v[90:91]
	v_pk_mul_f32 v[36:37], v[36:37], v[108:109]
	v_pk_mul_f32 v[38:39], v[38:39], v[94:95]
	v_pk_mul_f32 v[32:33], v[32:33], v[110:111]
	v_pk_mul_f32 v[34:35], v[34:35], v[96:97]
	v_cvt_pk_bf16_f32 v44, v44, v45
	v_cvt_pk_bf16_f32 v45, v46, v47
	v_cvt_pk_bf16_f32 v40, v40, v41
	v_cvt_pk_bf16_f32 v41, v42, v43
	v_cvt_pk_bf16_f32 v36, v36, v37
	v_cvt_pk_bf16_f32 v37, v38, v39
	v_cvt_pk_bf16_f32 v32, v32, v33
	v_cvt_pk_bf16_f32 v33, v34, v35
	global_store_dwordx2 v[100:101], v[44:45], off
	global_store_dwordx2 v[100:101], v[40:41], off offset:32
	global_store_dwordx2 v[100:101], v[36:37], off offset:64
	global_load_dwordx2 v[34:35], v[102:103], off
	v_add_u32_e32 v42, s26, v87
	global_store_dwordx2 v[100:101], v[32:33], off offset:96
	global_load_dword v32, v57, s[88:89] offset:128
	s_nop 0
	global_load_dwordx2 v[36:37], v[102:103], off offset:32
	global_load_dwordx2 v[38:39], v[102:103], off offset:64
	global_load_dwordx2 v[40:41], v[102:103], off offset:96
	v_lshlrev_b64 v[46:47], 12, v[98:99]
	v_mad_i64_i32 v[44:45], s[0:1], v42, s2, v[60:61]
	v_lshl_add_u64 v[46:47], s[16:17], 0, v[46:47]
	v_lshl_add_u64 v[46:47], v[46:47], 0, s[18:19]
	v_lshl_add_u64 v[44:45], v[44:45], 0, s[18:19]
	v_lshl_add_u64 v[46:47], v[46:47], 0, v[58:59]
	v_lshl_add_u64 v[44:45], v[44:45], 0, v[58:59]
	v_ashrrev_i32_e32 v43, 31, v42
	s_waitcnt vmcnt(5)
	v_lshlrev_b32_e32 v60, 16, v34
	v_and_b32_e32 v61, 0xffff0000, v34
	s_waitcnt vmcnt(3)
	v_pk_add_f32 v[28:29], v[28:29], v[32:33] op_sel_hi:[1,0]
	v_lshlrev_b32_e32 v34, 16, v35
	v_and_b32_e32 v35, 0xffff0000, v35
	v_pk_add_f32 v[30:31], v[30:31], v[32:33] op_sel_hi:[1,0]
	s_waitcnt vmcnt(2)
	v_lshlrev_b32_e32 v90, 16, v36
	v_and_b32_e32 v91, 0xffff0000, v36
	v_pk_add_f32 v[24:25], v[24:25], v[32:33] op_sel_hi:[1,0]
	v_lshlrev_b32_e32 v36, 16, v37
	v_and_b32_e32 v37, 0xffff0000, v37
	v_pk_add_f32 v[26:27], v[26:27], v[32:33] op_sel_hi:[1,0]
	s_waitcnt vmcnt(1)
	v_lshlrev_b32_e32 v92, 16, v38
	v_and_b32_e32 v93, 0xffff0000, v38
	v_pk_add_f32 v[20:21], v[20:21], v[32:33] op_sel_hi:[1,0]
	v_lshlrev_b32_e32 v38, 16, v39
	v_and_b32_e32 v39, 0xffff0000, v39
	v_pk_add_f32 v[22:23], v[22:23], v[32:33] op_sel_hi:[1,0]
	s_waitcnt vmcnt(0)
	v_lshlrev_b32_e32 v94, 16, v40
	v_and_b32_e32 v95, 0xffff0000, v40
	v_pk_add_f32 v[16:17], v[16:17], v[32:33] op_sel_hi:[1,0]
	v_lshlrev_b32_e32 v40, 16, v41
	v_and_b32_e32 v41, 0xffff0000, v41
	v_pk_add_f32 v[18:19], v[18:19], v[32:33] op_sel_hi:[1,0]
	v_pk_mul_f32 v[28:29], v[28:29], v[60:61]
	v_pk_mul_f32 v[30:31], v[30:31], v[34:35]
	v_pk_mul_f32 v[24:25], v[24:25], v[90:91]
	v_pk_mul_f32 v[26:27], v[26:27], v[36:37]
	v_pk_mul_f32 v[20:21], v[20:21], v[92:93]
	v_pk_mul_f32 v[22:23], v[22:23], v[38:39]
	v_pk_mul_f32 v[16:17], v[16:17], v[94:95]
	v_pk_mul_f32 v[18:19], v[18:19], v[40:41]
	v_cvt_pk_bf16_f32 v28, v28, v29
	v_cvt_pk_bf16_f32 v29, v30, v31
	v_cvt_pk_bf16_f32 v24, v24, v25
	v_cvt_pk_bf16_f32 v25, v26, v27
	v_cvt_pk_bf16_f32 v20, v20, v21
	v_cvt_pk_bf16_f32 v21, v22, v23
	v_cvt_pk_bf16_f32 v16, v16, v17
	v_cvt_pk_bf16_f32 v17, v18, v19
	global_store_dwordx2 v[46:47], v[28:29], off
	global_store_dwordx2 v[46:47], v[24:25], off offset:32
	global_store_dwordx2 v[46:47], v[20:21], off offset:64
	global_load_dwordx2 v[18:19], v[44:45], off
	v_lshlrev_b64 v[26:27], 12, v[42:43]
	global_store_dwordx2 v[46:47], v[16:17], off offset:96
	global_load_dword v16, v57, s[88:89] offset:192
	s_nop 0
	global_load_dwordx2 v[20:21], v[44:45], off offset:32
	global_load_dwordx2 v[22:23], v[44:45], off offset:64
	global_load_dwordx2 v[24:25], v[44:45], off offset:96
	v_lshl_add_u64 v[26:27], s[16:17], 0, v[26:27]
	v_lshl_add_u64 v[26:27], v[26:27], 0, s[18:19]
	v_lshl_add_u64 v[26:27], v[26:27], 0, v[58:59]
	s_waitcnt vmcnt(5)
	v_lshlrev_b32_e32 v28, 16, v18
	v_and_b32_e32 v29, 0xffff0000, v18
	s_waitcnt vmcnt(3)
	v_pk_add_f32 v[12:13], v[12:13], v[16:17] op_sel_hi:[1,0]
	v_lshlrev_b32_e32 v18, 16, v19
	v_and_b32_e32 v19, 0xffff0000, v19
	v_pk_add_f32 v[14:15], v[14:15], v[16:17] op_sel_hi:[1,0]
	s_waitcnt vmcnt(2)
	v_lshlrev_b32_e32 v30, 16, v20
	v_and_b32_e32 v31, 0xffff0000, v20
	v_pk_add_f32 v[8:9], v[8:9], v[16:17] op_sel_hi:[1,0]
	v_lshlrev_b32_e32 v20, 16, v21
	v_and_b32_e32 v21, 0xffff0000, v21
	v_pk_add_f32 v[10:11], v[10:11], v[16:17] op_sel_hi:[1,0]
	s_waitcnt vmcnt(1)
	v_lshlrev_b32_e32 v32, 16, v22
	v_and_b32_e32 v33, 0xffff0000, v22
	v_pk_add_f32 v[4:5], v[4:5], v[16:17] op_sel_hi:[1,0]
	v_lshlrev_b32_e32 v22, 16, v23
	v_and_b32_e32 v23, 0xffff0000, v23
	v_pk_add_f32 v[6:7], v[6:7], v[16:17] op_sel_hi:[1,0]
	s_waitcnt vmcnt(0)
	v_lshlrev_b32_e32 v34, 16, v24
	v_and_b32_e32 v35, 0xffff0000, v24
	v_pk_add_f32 v[0:1], v[0:1], v[16:17] op_sel_hi:[1,0]
	v_lshlrev_b32_e32 v24, 16, v25
	v_and_b32_e32 v25, 0xffff0000, v25
	v_pk_add_f32 v[2:3], v[2:3], v[16:17] op_sel_hi:[1,0]
	v_pk_mul_f32 v[12:13], v[12:13], v[28:29]
	v_pk_mul_f32 v[14:15], v[14:15], v[18:19]
	v_pk_mul_f32 v[8:9], v[8:9], v[30:31]
	v_pk_mul_f32 v[10:11], v[10:11], v[20:21]
	v_pk_mul_f32 v[4:5], v[4:5], v[32:33]
	v_pk_mul_f32 v[6:7], v[6:7], v[22:23]
	v_pk_mul_f32 v[0:1], v[0:1], v[34:35]
	v_pk_mul_f32 v[2:3], v[2:3], v[24:25]
	v_cvt_pk_bf16_f32 v12, v12, v13
	v_cvt_pk_bf16_f32 v13, v14, v15
	v_cvt_pk_bf16_f32 v8, v8, v9
	v_cvt_pk_bf16_f32 v9, v10, v11
	v_cvt_pk_bf16_f32 v4, v4, v5
	v_cvt_pk_bf16_f32 v5, v6, v7
	v_cvt_pk_bf16_f32 v0, v0, v1
	v_cvt_pk_bf16_f32 v1, v2, v3
	global_store_dwordx2 v[26:27], v[12:13], off
	global_store_dwordx2 v[26:27], v[8:9], off offset:32
	global_store_dwordx2 v[26:27], v[4:5], off offset:64
	global_store_dwordx2 v[26:27], v[0:1], off offset:96
	s_barrier
	s_cbranch_scc0 .LBB0_354
